# GDN fwd substitution: identity-initialised T, exec-masked row update, two accumulators (8 fewer VALU per row pair)
# speedup vs baseline: 1.0538x; 1.0113x over previous
; #define LAS __attribute__((address_space(3)))
; __device__ __forceinline__ float fexp(float x) { return __builtin_amdgcn_exp2f(x * 1.4426950408889634f); }
; __device__ __forceinline__ v2u pack4(const f32x4 v) { v2u r; r.x = pk2(v[0], v[1]); r.y = pk2(v[2], v[3]); return r; }
;     ...
;     for (int k2 = 0; k2 < 2; ++k2) {
;         const int tt = 2 * w + k2, mt = tt >> 2, nt = tt & 3;
;         f32x4 accG = {0.f, 0.f, 0.f, 0.f}, accQ = {0.f, 0.f, 0.f, 0.f};
;         accG = mma_ll<2>(Ks + mt * 16 * 72, 72, Ks + nt * 16 * 72, 72, accG, lane);
;         accQ = mma_ll<2>(Ks + mt * 16 * 72, 72, Qs + nt * 16 * 72, 72, accQ, lane);
;         const int n = nt * 16 + lr, m0 = mt * 16 + 4 * lq;
; #pragma unroll
;         for (int d = 0; d < 2; ++d) {
;             const float gcn = gcS[d * 64 + n], bn = bS[d * 64 + n];
;             f32x4 av, tv;
; #pragma unroll
;             for (int i = 0; i < 4; ++i) { const int m = m0 + i; const float gcm = gcS[d * 64 + m];
;                 const bool strict = d == 0 ? (m < n) : (m > n); const bool incl = d == 0 ? (m <= n) : (m >= n);
;                 const float e = fexp(incl ? (gcn - gcm) : 0.f);
;                 av[i] = strict ? bn * accG[i] * e : 0.f; tv[i] = incl ? 0.125f * accQ[i] * e : 0.f; }
; #pragma unroll
;             for (int i = 0; i < 4; ++i) { const int si = d ? 63 - n : n, sj = d ? 63 - (m0 + i) : m0 + i; As[d * 4352 + (si >> 1) * 136 + sj * 2 + (si & 1)] = av[i]; }
;             *(LAS v2u*)(At + d * 4608 + n * 72 + m0) = pack4(tv);
;         }
;     }
.LBB0_642:
	s_lshl_b32 s0, s28, 1
	s_and_b32 s1, s0, 2
	s_lshl_b32 s0, s28, 3
	s_and_b32 s3, s0, -16
	v_lshrrev_b32_e32 v7, 1, v52
	v_and_b32_e32 v109, 15, v52
	s_mul_i32 s4, s3, 0x90
	v_and_b32_e32 v0, 24, v7
	v_lshrrev_b32_e32 v13, 4, v53
	s_add_i32 s4, s4, 0
	v_mul_u32_u24_e32 v113, 0x90, v109
	v_lshlrev_b32_e32 v117, 1, v0
	v_add3_u32 v12, s4, v113, v117
	s_movk_i32 s4, 0x90
	v_lshlrev_b32_e32 v17, 2, v13
	v_mad_u32_u24 v121, v109, s4, 0
	v_or_b32_e32 v15, s3, v17
	v_readlane_b32 s3, v253, 55
	v_add_u32_e32 v14, v121, v117
	s_waitcnt lgkmcnt(0)
	v_lshl_add_u32 v16, v15, 1, s3
	s_mul_i32 s3, s1, 0x900
	s_barrier
	v_add_u32_e32 v6, s3, v14
	ds_read_b128 v[8:11], v12 offset:9216
	ds_read_b128 v[2:5], v6 offset:9216
	ds_read_b128 v[22:25], v12 offset:9280
	ds_read_b128 v[26:29], v6 offset:9280
	s_waitcnt lgkmcnt(2)
	v_mfma_f32_16x16x32_bf16 v[2:5], v[8:11], v[2:5], 0
	v_lshl_or_b32 v20, s1, 4, v109
	v_cmp_gt_i32_e64 s[40:41], v15, v20
	v_cmp_lt_i32_e32 vcc, v15, v20
	s_waitcnt lgkmcnt(0)
	v_mfma_f32_16x16x32_bf16 v[2:5], v[22:25], v[26:29], v[2:5]
	ds_read_b128 v[26:29], v6
	v_or_b32_e32 v34, 2, v15
	v_cmp_gt_i32_e64 s[46:47], v34, v20
	s_waitcnt lgkmcnt(0)
	v_mfma_f32_16x16x32_bf16 v[8:11], v[8:11], v[26:29], 0
	ds_read_b128 v[26:29], v6 offset:64
	v_lshl_add_u32 v6, v15, 2, 0
	v_or_b32_e32 v36, 3, v15
	s_waitcnt lgkmcnt(0)
	v_mfma_f32_16x16x32_bf16 v[8:11], v[22:25], v[26:29], v[8:11]
	v_lshl_add_u32 v27, v20, 2, 0
	ds_read_b32 v28, v27 offset:37888
	ds_read_b32 v29, v27 offset:37376
	ds_read_b128 v[22:25], v6 offset:37888
	s_nop 3
	v_mul_f32_e32 v31, 0x3e000000, v8
	v_mul_f32_e32 v33, 0x3e000000, v9
	v_mul_f32_e32 v35, 0x3e000000, v10
	s_waitcnt lgkmcnt(1)
	v_mul_f32_e32 v30, v2, v29
	s_waitcnt lgkmcnt(0)
	v_sub_f32_e32 v22, v28, v22
	v_mul_f32_e32 v22, 0x3fb8aa3b, v22
	v_cndmask_b32_e64 v22, v22, 0, s[40:41]
	v_exp_f32_e32 v22, v22
	v_cmp_gt_i32_e64 s[50:51], v36, v20
	v_or_b32_e32 v32, 1, v15
	v_and_b32_e32 v18, 1, v52
	v_mul_f32_e32 v30, v30, v22
	v_mul_f32_e32 v8, v31, v22
	v_sub_f32_e32 v22, v28, v23
	v_mul_f32_e32 v22, 0x3fb8aa3b, v22
	v_cndmask_b32_e32 v22, 0, v22, vcc
	v_exp_f32_e32 v22, v22
	v_mul_f32_e32 v23, v3, v29
	v_mad_u32_u24 v26, v20, s4, v16
	v_cmp_lt_i32_e64 s[42:43], v32, v20
	v_mul_f32_e32 v23, v23, v22
	v_mul_f32_e32 v9, v33, v22
	v_sub_f32_e32 v22, v28, v24
	v_mul_f32_e32 v22, 0x3fb8aa3b, v22
	v_cndmask_b32_e64 v22, v22, 0, s[46:47]
	v_exp_f32_e32 v22, v22
	v_mul_f32_e32 v24, v4, v29
	v_cmp_lt_i32_e64 s[44:45], v34, v20
	v_cmp_lt_i32_e64 s[48:49], v36, v20
	v_mul_f32_e32 v24, v24, v22
	v_mul_f32_e32 v10, v35, v22
	v_sub_f32_e32 v22, v28, v25
	v_mul_f32_e32 v22, 0x3fb8aa3b, v22
	v_cndmask_b32_e64 v22, v22, 0, s[50:51]
	v_exp_f32_e32 v22, v22
	v_mul_f32_e32 v25, v5, v29
	v_mul_f32_e32 v28, 0x3e000000, v11
	v_lshrrev_b32_e32 v20, 1, v20
	v_mul_f32_e32 v25, v25, v22
	v_mul_f32_e32 v11, v28, v22
	v_mul_u32_u24_e32 v22, 0x220, v20
	v_lshlrev_b32_e32 v18, 2, v18
	v_lshlrev_b32_e32 v0, 3, v15
	v_add3_u32 v22, 0, v22, v18
	v_cndmask_b32_e32 v30, 0, v30, vcc
	v_add_u32_e32 v29, v22, v0
	ds_write_b32 v29, v30 offset:38912
	v_lshlrev_b32_e32 v30, 3, v32
	v_cndmask_b32_e64 v8, v8, 0, s[40:41]
	v_cndmask_b32_e64 v23, 0, v23, s[42:43]
	v_cndmask_b32_e32 v9, 0, v9, vcc
	v_cndmask_b32_e64 v10, v10, 0, s[46:47]
	v_cndmask_b32_e64 v11, v11, 0, s[50:51]
	v_add_u32_e32 v29, v22, v30
	v_lshlrev_b32_e32 v37, 3, v34
	v_lshlrev_b32_e32 v38, 3, v36
	v_cndmask_b32_e64 v24, 0, v24, s[44:45]
	v_cndmask_b32_e64 v25, 0, v25, s[48:49]
	ds_write_b32 v29, v23 offset:38912
	v_add_u32_e32 v23, v22, v37
	v_add_u32_e32 v22, v22, v38
	v_cvt_pk_bf16_f32 v8, v8, v9
	v_cvt_pk_bf16_f32 v9, v10, v11
	ds_write_b32 v23, v24 offset:38912
	ds_write_b32 v22, v25 offset:38912
	ds_write_b64 v26, v[8:9]
	ds_read_b32 v22, v27 offset:38144
	ds_read_b32 v23, v27 offset:37632
	ds_read_b128 v[8:11], v6 offset:38144
	v_bitop3_b32 v19, v52, 1, v52 bitop3:0xc
	v_xor_b32_e32 v20, 31, v20
	v_mul_u32_u24_e32 v20, 0x220, v20
	s_waitcnt lgkmcnt(1)
	v_mul_f32_e32 v2, v2, v23
	s_waitcnt lgkmcnt(0)
	v_sub_f32_e32 v8, v22, v8
	v_mul_f32_e32 v8, 0x3fb8aa3b, v8
	v_sub_f32_e32 v9, v22, v9
	v_cndmask_b32_e64 v8, v8, 0, vcc
	v_mul_f32_e32 v9, 0x3fb8aa3b, v9
	v_sub_f32_e32 v10, v22, v10
	v_exp_f32_e32 v8, v8
	v_cndmask_b32_e64 v9, v9, 0, s[42:43]
	v_mul_f32_e32 v10, 0x3fb8aa3b, v10
	v_sub_f32_e32 v11, v22, v11
	v_exp_f32_e32 v9, v9
	v_cndmask_b32_e64 v10, v10, 0, s[44:45]
	v_mul_f32_e32 v11, 0x3fb8aa3b, v11
	v_exp_f32_e32 v10, v10
	v_cndmask_b32_e64 v11, v11, 0, s[48:49]
	v_exp_f32_e32 v11, v11
	v_lshlrev_b32_e32 v19, 2, v19
	v_mul_f32_e32 v2, v2, v8
	v_mul_f32_e32 v3, v3, v23
	v_add3_u32 v20, 0, v20, v19
	v_cndmask_b32_e64 v2, 0, v2, s[40:41]
	v_mul_f32_e32 v3, v3, v9
	v_mul_f32_e32 v4, v4, v23
	v_sub_u32_e32 v22, v20, v0
	v_cndmask_b32_e64 v3, v3, 0, vcc
	v_mul_f32_e32 v4, v4, v10
	v_mul_f32_e32 v5, v5, v23
	ds_write_b32 v22, v2 offset:56824
	v_sub_u32_e32 v2, v20, v30
	v_mul_f32_e32 v8, v31, v8
	v_mul_f32_e32 v9, v33, v9
	v_cndmask_b32_e64 v4, 0, v4, s[46:47]
	v_mul_f32_e32 v10, v35, v10
	v_mul_f32_e32 v5, v5, v11
	v_mul_f32_e32 v11, v28, v11
	ds_write_b32 v2, v3 offset:56824
	v_sub_u32_e32 v2, v20, v37
	v_cndmask_b32_e64 v8, v8, 0, vcc
	v_cndmask_b32_e64 v9, v9, 0, s[42:43]
	v_cndmask_b32_e64 v10, v10, 0, s[44:45]
	v_cndmask_b32_e64 v5, 0, v5, s[50:51]
	v_cndmask_b32_e64 v11, v11, 0, s[48:49]
	ds_write_b32 v2, v4 offset:56824
	v_sub_u32_e32 v2, v20, v38
	ds_write_b32 v2, v5 offset:56824
	v_cvt_pk_bf16_f32 v2, v8, v9
	v_cvt_pk_bf16_f32 v3, v10, v11
	s_or_b32 s1, s1, 1
	ds_write_b64 v26, v[2:3] offset:9216
	s_mul_i32 s3, s1, 0x900
	v_add_u32_e32 v14, s3, v14
	ds_read_b128 v[8:11], v12 offset:9216
	ds_read_b128 v[2:5], v14 offset:9216
	ds_read_b128 v[22:25], v12 offset:9280
	ds_read_b128 v[26:29], v14 offset:9280
	s_waitcnt lgkmcnt(2)
; #define LAS __attribute__((address_space(3)))
; __device__ __forceinline__ float fexp(float x) { return __builtin_amdgcn_exp2f(x * 1.4426950408889634f); }
; __device__ __forceinline__ v2u pack4(const f32x4 v) { v2u r; r.x = pk2(v[0], v[1]); r.y = pk2(v[2], v[3]); return r; }
;     ...
;     for (int k2 = 0; k2 < 2; ++k2) {
;         const int tt = 2 * w + k2, mt = tt >> 2, nt = tt & 3;
;         f32x4 accG = {0.f, 0.f, 0.f, 0.f}, accQ = {0.f, 0.f, 0.f, 0.f};
;         accG = mma_ll<2>(Ks + mt * 16 * 72, 72, Ks + nt * 16 * 72, 72, accG, lane);
;         accQ = mma_ll<2>(Ks + mt * 16 * 72, 72, Qs + nt * 16 * 72, 72, accQ, lane);
;         const int n = nt * 16 + lr, m0 = mt * 16 + 4 * lq;
; #pragma unroll
;         for (int d = 0; d < 2; ++d) {
;             const float gcn = gcS[d * 64 + n], bn = bS[d * 64 + n];
;             f32x4 av, tv;
; #pragma unroll
;             for (int i = 0; i < 4; ++i) { const int m = m0 + i; const float gcm = gcS[d * 64 + m];
;                 const bool strict = d == 0 ? (m < n) : (m > n); const bool incl = d == 0 ? (m <= n) : (m >= n);
;                 const float e = fexp(incl ? (gcn - gcm) : 0.f);
;                 av[i] = strict ? bn * accG[i] * e : 0.f; tv[i] = incl ? 0.125f * accQ[i] * e : 0.f; }
; #pragma unroll
;             for (int i = 0; i < 4; ++i) { const int si = d ? 63 - n : n, sj = d ? 63 - (m0 + i) : m0 + i; As[d * 4352 + (si >> 1) * 136 + sj * 2 + (si & 1)] = av[i]; }
;             *(LAS v2u*)(At + d * 4608 + n * 72 + m0) = pack4(tv);
;         }
;     }
;     __syncthreads();
	v_mfma_f32_16x16x32_bf16 v[2:5], v[8:11], v[2:5], 0
	v_lshl_or_b32 v12, s1, 4, v109
	v_cmp_lt_i32_e32 vcc, v15, v12
	v_cmp_gt_i32_e64 s[40:41], v15, v12
	s_waitcnt lgkmcnt(0)
	v_mfma_f32_16x16x32_bf16 v[2:5], v[22:25], v[26:29], v[2:5]
	ds_read_b128 v[26:29], v14
	v_cmp_gt_i32_e64 s[46:47], v34, v12
	v_cmp_gt_i32_e64 s[50:51], v36, v12
	s_waitcnt lgkmcnt(0)
	v_mfma_f32_16x16x32_bf16 v[8:11], v[8:11], v[26:29], 0
	ds_read_b128 v[26:29], v14 offset:64
	v_mad_u32_u24 v14, v12, s4, v16
	v_lshl_add_u32 v16, v12, 2, 0
	s_waitcnt lgkmcnt(0)
	v_mfma_f32_16x16x32_bf16 v[8:11], v[22:25], v[26:29], v[8:11]
	ds_read_b32 v20, v16 offset:37888
	ds_read_b32 v26, v16 offset:37376
	ds_read_b128 v[22:25], v6 offset:37888
	v_cmp_lt_i32_e64 s[42:43], v32, v12
	v_cmp_lt_i32_e64 s[44:45], v34, v12
	s_nop 2
	v_mul_f32_e32 v27, 0x3e000000, v8
	v_mul_f32_e32 v28, 0x3e000000, v9
	s_waitcnt lgkmcnt(0)
	v_sub_f32_e32 v15, v20, v22
	v_mul_f32_e32 v15, 0x3fb8aa3b, v15
	v_cndmask_b32_e64 v15, v15, 0, s[40:41]
	v_exp_f32_e32 v15, v15
	v_mul_f32_e32 v22, v2, v26
	v_mul_f32_e32 v29, 0x3e000000, v10
	v_cmp_lt_i32_e64 s[48:49], v36, v12
	v_mul_f32_e32 v22, v22, v15
	v_mul_f32_e32 v8, v27, v15
	v_sub_f32_e32 v15, v20, v23
	v_mul_f32_e32 v15, 0x3fb8aa3b, v15
	v_cndmask_b32_e32 v15, 0, v15, vcc
	v_exp_f32_e32 v15, v15
	v_mul_f32_e32 v23, v3, v26
	v_lshrrev_b32_e32 v12, 1, v12
	v_cndmask_b32_e32 v22, 0, v22, vcc
	v_mul_f32_e32 v23, v23, v15
	v_mul_f32_e32 v9, v28, v15
	v_sub_f32_e32 v15, v20, v24
	v_mul_f32_e32 v15, 0x3fb8aa3b, v15
	v_cndmask_b32_e64 v15, v15, 0, s[46:47]
	v_exp_f32_e32 v15, v15
	v_mul_f32_e32 v24, v4, v26
	v_cndmask_b32_e64 v8, v8, 0, s[40:41]
	v_cndmask_b32_e64 v23, 0, v23, s[42:43]
	v_mul_f32_e32 v24, v24, v15
	v_mul_f32_e32 v10, v29, v15
	v_sub_f32_e32 v15, v20, v25
	v_mul_f32_e32 v15, 0x3fb8aa3b, v15
	v_cndmask_b32_e64 v15, v15, 0, s[50:51]
	v_exp_f32_e32 v15, v15
	v_mul_f32_e32 v20, v5, v26
	v_mul_f32_e32 v25, 0x3e000000, v11
	v_cndmask_b32_e32 v9, 0, v9, vcc
	v_mul_f32_e32 v20, v20, v15
	v_mul_f32_e32 v11, v25, v15
	v_mul_u32_u24_e32 v15, 0x220, v12
	v_add3_u32 v15, 0, v15, v18
	v_add_u32_e32 v18, v15, v0
	v_cndmask_b32_e64 v10, v10, 0, s[46:47]
	v_cndmask_b32_e64 v11, v11, 0, s[50:51]
	ds_write_b32 v18, v22 offset:38912
	v_add_u32_e32 v18, v15, v30
	v_cndmask_b32_e64 v24, 0, v24, s[44:45]
	v_cndmask_b32_e64 v20, 0, v20, s[48:49]
	ds_write_b32 v18, v23 offset:38912
	v_add_u32_e32 v18, v15, v37
	v_add_u32_e32 v15, v15, v38
	v_cvt_pk_bf16_f32 v8, v8, v9
	v_cvt_pk_bf16_f32 v9, v10, v11
	ds_write_b32 v18, v24 offset:38912
	ds_write_b32 v15, v20 offset:38912
	ds_write_b64 v14, v[8:9]
	ds_read_b32 v15, v16 offset:38144
	ds_read_b32 v16, v16 offset:37632
	ds_read_b128 v[8:11], v6 offset:38144
	s_movk_i32 s92, 0x90
	s_waitcnt lgkmcnt(1)
	v_mul_f32_e32 v2, v2, v16
	s_waitcnt lgkmcnt(0)
	v_sub_f32_e32 v6, v15, v8
	v_mul_f32_e32 v6, 0x3fb8aa3b, v6
	v_sub_f32_e32 v8, v15, v9
	v_cndmask_b32_e64 v6, v6, 0, vcc
	v_mul_f32_e32 v8, 0x3fb8aa3b, v8
	v_sub_f32_e32 v9, v15, v10
	v_sub_f32_e32 v10, v15, v11
	v_exp_f32_e32 v6, v6
	v_cndmask_b32_e64 v8, v8, 0, s[42:43]
	v_mul_f32_e32 v9, 0x3fb8aa3b, v9
	v_mul_f32_e32 v10, 0x3fb8aa3b, v10
	v_exp_f32_e32 v8, v8
	v_cndmask_b32_e64 v9, v9, 0, s[44:45]
	v_cndmask_b32_e64 v10, v10, 0, s[48:49]
	v_exp_f32_e32 v9, v9
	v_exp_f32_e32 v10, v10
	v_xor_b32_e32 v11, 31, v12
	v_mul_u32_u24_e32 v11, 0x220, v11
	v_mul_f32_e32 v2, v2, v6
	v_mul_f32_e32 v3, v3, v16
	v_add3_u32 v11, 0, v11, v19
	v_cndmask_b32_e64 v2, 0, v2, s[40:41]
	v_mul_f32_e32 v3, v3, v8
	v_mul_f32_e32 v4, v4, v16
	v_mul_f32_e32 v5, v5, v16
	v_sub_u32_e32 v0, v11, v0
	v_mul_f32_e32 v6, v27, v6
	v_cndmask_b32_e64 v3, v3, 0, vcc
	v_mul_f32_e32 v8, v28, v8
	v_mul_f32_e32 v4, v4, v9
	v_mul_f32_e32 v9, v29, v9
	v_mul_f32_e32 v5, v5, v10
	v_mul_f32_e32 v10, v25, v10
	ds_write_b32 v0, v2 offset:56824
	v_sub_u32_e32 v0, v11, v30
	v_cndmask_b32_e64 v6, v6, 0, vcc
	v_cndmask_b32_e64 v8, v8, 0, s[42:43]
	v_cndmask_b32_e64 v4, 0, v4, s[46:47]
	v_cndmask_b32_e64 v9, v9, 0, s[44:45]
	v_cndmask_b32_e64 v10, v10, 0, s[48:49]
	ds_write_b32 v0, v3 offset:56824
	v_sub_u32_e32 v0, v11, v37
	v_cndmask_b32_e64 v5, 0, v5, s[50:51]
	ds_write_b32 v0, v4 offset:56824
	v_sub_u32_e32 v0, v11, v38
	v_cvt_pk_bf16_f32 v2, v6, v8
	v_cvt_pk_bf16_f32 v3, v9, v10
	s_andn2_b64 vcc, exec, s[10:11]
	ds_write_b32 v0, v5 offset:56824
	ds_write_b64 v14, v[2:3] offset:9216
	s_waitcnt lgkmcnt(0)
	s_barrier
; #define LAS __attribute__((address_space(3)))
; __device__ __forceinline__ float fexp(float x) { return __builtin_amdgcn_exp2f(x * 1.4426950408889634f); }
;     ...
;     if (w < 2) {
;         const int d = w; const LAS float* Ad = As + d * 4352;
;         float tr[64]; int lane_o = lane;
; #pragma unroll
;         for (int ip = 0; ip < 32; ++ip) {
;             const int i0 = 2 * ip;
;             f32x4 rv[32];
; #pragma unroll
;             for (int jp = 0; jp <= ip; ++jp) rv[jp] = *(const LAS f32x4*)(Ad + ip * 136 + 4 * jp);
;             asm volatile("" : "+v"(lane_o) :: "memory");
;             f32x2_ a0 = {0.f, 0.f}, a1 = {0.f, 0.f}, a2 = {0.f, 0.f}, a3 = {0.f, 0.f};
; #pragma unroll
;             for (int jp = 0; jp < ip; ++jp) {
;                 const f32x2_ ta = {tr[2 * jp], tr[2 * jp]}, tb = {tr[2 * jp + 1], tr[2 * jp + 1]};
;                 const f32x2_ va = {rv[jp][0], rv[jp][1]}, vb = {rv[jp][2], rv[jp][3]};
;                 if (jp & 1) { a2 += va * ta; a3 += vb * tb; } else { a0 += va * ta; a1 += vb * tb; }
;             }
;             const f32x2_ sum = (a0 + a1) + (a2 + a3);
;             const float t0 = (lane_o == i0 ? 1.f : 0.f) - sum[0];
;             tr[i0] = t0;
;             tr[i0 + 1] = (lane_o == i0 + 1 ? 1.f : 0.f) - sum[1] - rv[ip][1] * t0;
;         }
;         const int pb = d ? 63 - lane : lane; const float sb = bS[d * 64 + pb], sbe = sb * fexp(gcS[d * 64 + pb]);
	s_waitcnt vmcnt(0) lgkmcnt(0)
	v_mbcnt_lo_u32_b32 v0, -1, 0
	v_mbcnt_hi_u32_b32 v0, -1, v0
	s_and_b32 s1, s28, 1
	s_lshr_b32 s3, s28, 1
	s_mov_b32 s4, 0x11111111
	s_mov_b32 s5, 0x11111111
	s_mov_b32 s6, 0x22222222
	s_mov_b32 s7, 0x22222222
	s_mov_b32 s8, 0x44444444
	s_mov_b32 s9, 0x44444444
	s_mov_b32 s10, 0x88888888
	s_mov_b32 s11, 0x88888888
	v_and_b32_e32 v6, 3, v0
	v_lshrrev_b32_e32 v12, 2, v0
	s_lshl_b32 s29, s3, 4
	v_add_u32_e32 v12, s29, v12
	s_mul_i32 s29, s1, 0x4400
	s_add_i32 s29, s29, 0x9800
	v_lshlrev_b32_e32 v14, 4, v6
	v_add_u32_e32 v14, s29, v14
	s_mul_i32 s29, s1, 0x3f
	v_xor_b32_e32 v16, s29, v12
	s_lshl_b32 s29, s1, 8
	s_add_i32 s29, s29, 0x9200
	v_lshl_add_u32 v223, v16, 2, s29
	ds_read_b32 v56, v223
	ds_read_b32 v224, v223 offset:512
	s_mul_i32 s29, s1, 0x3
	v_xor_b32_e32 v223, s29, v6
	v_mul_u32_u24_e32 v223, 0x120, v223
	v_lshl_add_u32 v64, v16, 1, v223
	s_mul_i32 s29, s1, 0x4800
	s_add_i32 s29, s29, 0x12800
	v_add_u32_e32 v64, s29, v64
	v_lshlrev_b32_e32 v223, 1, v6
	v_sub_u32_e32 v68, v12, v223
	v_add_u32_e32 v112, -1, v68
	v_cmp_eq_u32_e64 s[12:13], 0, v68
	v_cmp_eq_u32_e64 s[14:15], 0, v112
	s_nop 0
	v_cndmask_b32_e64 v2, 0, 1.0, s[12:13]
	v_cndmask_b32_e64 v3, 0, 1.0, s[14:15]
	v_cmp_eq_u32_e64 s[12:13], 8, v68
	v_cmp_eq_u32_e64 s[14:15], 8, v112
	s_nop 0
	v_cndmask_b32_e64 v4, 0, 1.0, s[12:13]
	v_cndmask_b32_e64 v5, 0, 1.0, s[14:15]
	v_cmp_eq_u32_e64 s[12:13], 16, v68
	v_cmp_eq_u32_e64 s[14:15], 16, v112
	s_nop 0
	v_cndmask_b32_e64 v8, 0, 1.0, s[12:13]
	v_cndmask_b32_e64 v9, 0, 1.0, s[14:15]
	v_cmp_eq_u32_e64 s[12:13], 24, v68
	v_cmp_eq_u32_e64 s[14:15], 24, v112
	s_nop 0
	v_cndmask_b32_e64 v10, 0, 1.0, s[12:13]
	v_cndmask_b32_e64 v11, 0, 1.0, s[14:15]
	v_cmp_eq_u32_e64 s[12:13], 32, v68
	v_cmp_eq_u32_e64 s[14:15], 32, v112
	s_nop 0
	v_cndmask_b32_e64 v18, 0, 1.0, s[12:13]
	v_cndmask_b32_e64 v19, 0, 1.0, s[14:15]
	v_cmp_eq_u32_e64 s[12:13], 40, v68
	v_cmp_eq_u32_e64 s[14:15], 40, v112
	s_nop 0
	v_cndmask_b32_e64 v50, 0, 1.0, s[12:13]
	v_cndmask_b32_e64 v51, 0, 1.0, s[14:15]
	v_cmp_eq_u32_e64 s[12:13], 48, v68
	v_cmp_eq_u32_e64 s[14:15], 48, v112
	s_nop 0
	v_cndmask_b32_e64 v54, 0, 1.0, s[12:13]
	v_cndmask_b32_e64 v55, 0, 1.0, s[14:15]
	v_cmp_eq_u32_e64 s[12:13], 56, v68
	v_cmp_eq_u32_e64 s[14:15], 56, v112
	s_nop 0
	v_cndmask_b32_e64 v58, 0, 1.0, s[12:13]
	v_cndmask_b32_e64 v59, 0, 1.0, s[14:15]
	s_waitcnt lgkmcnt(0)
	v_mul_f32_e32 v224, 0x3fb8aa3b, v224
	v_exp_f32_e32 v224, v224
	s_nop 0
	v_mul_f32_e32 v60, v56, v224
	s_cmp_eq_u32 s3, 0
	s_cbranch_scc1 .Lfs_ent0
	s_cmp_eq_u32 s3, 1
	s_cbranch_scc1 .Lfs_ent1
	s_cmp_eq_u32 s3, 2
	s_cbranch_scc1 .Lfs_ent2
	s_branch .Lfs_ent3

; #define LAS __attribute__((address_space(3)))
;     ...
;         for (int ip = 0; ip < 32; ++ip) {
;             const int i0 = 2 * ip;
;             f32x4 rv[32];
; #pragma unroll
;             for (int jp = 0; jp <= ip; ++jp) rv[jp] = *(const LAS f32x4*)(Ad + ip * 136 + 4 * jp);
;             asm volatile("" : "+v"(lane_o) :: "memory");
;             f32x2_ a0 = {0.f, 0.f}, a1 = {0.f, 0.f}, a2 = {0.f, 0.f}, a3 = {0.f, 0.f};
; #pragma unroll
;             for (int jp = 0; jp < ip; ++jp) {
;                 const f32x2_ ta = {tr[2 * jp], tr[2 * jp]}, tb = {tr[2 * jp + 1], tr[2 * jp + 1]};
;                 const f32x2_ va = {rv[jp][0], rv[jp][1]}, vb = {rv[jp][2], rv[jp][3]};
;                 if (jp & 1) { a2 += va * ta; a3 += vb * tb; } else { a0 += va * ta; a1 += vb * tb; }
;             }
;             const f32x2_ sum = (a0 + a1) + (a2 + a3);
;             const float t0 = (lane_o == i0 ? 1.f : 0.f) - sum[0];
;             tr[i0] = t0;
;             tr[i0 + 1] = (lane_o == i0 + 1 ? 1.f : 0.f) - sum[1] - rv[ip][1] * t0;
;         }
.Lfs_row0:
	ds_read_b128 v[122:125], v14 offset:544
	s_waitcnt lgkmcnt(1)
	v_pk_fma_f32 v[62:63], v[70:71], v[2:3], 0 op_sel_hi:[1,0,0]
	v_pk_fma_f32 v[66:67], v[72:73], v[2:3], 0 op_sel:[0,1,0] op_sel_hi:[1,1,0]
	v_pk_add_f32 v[62:63], v[62:63], v[66:67]
	s_nop 1
	v_add_f32_dpp v62, v62, v62 quad_perm:[1,0,3,2] row_mask:0xf bank_mask:0xf bound_ctrl:1
	v_add_f32_dpp v63, v63, v63 quad_perm:[1,0,3,2] row_mask:0xf bank_mask:0xf bound_ctrl:1
	s_nop 0
	v_add_f32_dpp v62, v62, v62 quad_perm:[2,3,0,1] row_mask:0xf bank_mask:0xf bound_ctrl:1
	v_add_f32_dpp v63, v63, v63 quad_perm:[2,3,0,1] row_mask:0xf bank_mask:0xf bound_ctrl:1
	s_mov_b64 exec, s[4:5]
	v_sub_f32_e32 v2, v2, v62
	v_sub_f32_e32 v3, v3, v63
	v_fma_f32 v3, v71, v62, v3
	s_mov_b64 exec, -1
.Lfs_row1:
	ds_read_b128 v[70:73], v14 offset:1088
	s_waitcnt lgkmcnt(1)
	v_pk_fma_f32 v[62:63], v[122:123], v[2:3], 0 op_sel_hi:[1,0,0]
	v_pk_fma_f32 v[66:67], v[124:125], v[2:3], 0 op_sel:[0,1,0] op_sel_hi:[1,1,0]
	v_pk_add_f32 v[62:63], v[62:63], v[66:67]
	s_nop 1
	v_add_f32_dpp v62, v62, v62 quad_perm:[1,0,3,2] row_mask:0xf bank_mask:0xf bound_ctrl:1
	v_add_f32_dpp v63, v63, v63 quad_perm:[1,0,3,2] row_mask:0xf bank_mask:0xf bound_ctrl:1
	s_nop 0
	v_add_f32_dpp v62, v62, v62 quad_perm:[2,3,0,1] row_mask:0xf bank_mask:0xf bound_ctrl:1
	v_add_f32_dpp v63, v63, v63 quad_perm:[2,3,0,1] row_mask:0xf bank_mask:0xf bound_ctrl:1
	s_mov_b64 exec, s[6:7]
	v_sub_f32_e32 v2, v2, v62
	v_sub_f32_e32 v3, v3, v63
	v_fma_f32 v3, v123, v62, v3
	s_mov_b64 exec, -1
.Lfs_row2:
	ds_read_b128 v[122:125], v14 offset:1632
	s_waitcnt lgkmcnt(1)
	v_pk_fma_f32 v[62:63], v[70:71], v[2:3], 0 op_sel_hi:[1,0,0]
	v_pk_fma_f32 v[66:67], v[72:73], v[2:3], 0 op_sel:[0,1,0] op_sel_hi:[1,1,0]
	v_pk_add_f32 v[62:63], v[62:63], v[66:67]
	s_nop 1
	v_add_f32_dpp v62, v62, v62 quad_perm:[1,0,3,2] row_mask:0xf bank_mask:0xf bound_ctrl:1
	v_add_f32_dpp v63, v63, v63 quad_perm:[1,0,3,2] row_mask:0xf bank_mask:0xf bound_ctrl:1
	s_nop 0
	v_add_f32_dpp v62, v62, v62 quad_perm:[2,3,0,1] row_mask:0xf bank_mask:0xf bound_ctrl:1
	v_add_f32_dpp v63, v63, v63 quad_perm:[2,3,0,1] row_mask:0xf bank_mask:0xf bound_ctrl:1
	s_mov_b64 exec, s[8:9]
	v_sub_f32_e32 v2, v2, v62
	v_sub_f32_e32 v3, v3, v63
	v_fma_f32 v3, v71, v62, v3
	s_mov_b64 exec, -1
.Lfs_row3:
	ds_read_b128 v[70:73], v14 offset:2176
	ds_read_b128 v[74:77], v14 offset:2240
	s_waitcnt lgkmcnt(2)
	v_pk_fma_f32 v[62:63], v[122:123], v[2:3], 0 op_sel_hi:[1,0,0]
	v_pk_fma_f32 v[66:67], v[124:125], v[2:3], 0 op_sel:[0,1,0] op_sel_hi:[1,1,0]
	v_pk_add_f32 v[62:63], v[62:63], v[66:67]
	s_nop 1
	v_add_f32_dpp v62, v62, v62 quad_perm:[1,0,3,2] row_mask:0xf bank_mask:0xf bound_ctrl:1
	v_add_f32_dpp v63, v63, v63 quad_perm:[1,0,3,2] row_mask:0xf bank_mask:0xf bound_ctrl:1
	s_nop 0
	v_add_f32_dpp v62, v62, v62 quad_perm:[2,3,0,1] row_mask:0xf bank_mask:0xf bound_ctrl:1
	v_add_f32_dpp v63, v63, v63 quad_perm:[2,3,0,1] row_mask:0xf bank_mask:0xf bound_ctrl:1
	s_mov_b64 exec, s[10:11]
	v_sub_f32_e32 v2, v2, v62
	v_sub_f32_e32 v3, v3, v63
	v_fma_f32 v3, v123, v62, v3
	s_mov_b64 exec, -1
.Lfs_row4:
	ds_read_b128 v[122:125], v14 offset:2720
	ds_read_b128 v[126:129], v14 offset:2784
	s_waitcnt lgkmcnt(2)
	v_pk_fma_f32 v[62:63], v[74:75], v[4:5], 0 op_sel_hi:[1,0,0]
	v_pk_fma_f32 v[66:67], v[76:77], v[4:5], 0 op_sel:[0,1,0] op_sel_hi:[1,1,0]
	v_pk_fma_f32 v[62:63], v[70:71], v[2:3], v[62:63] op_sel_hi:[1,0,1]
	v_pk_fma_f32 v[66:67], v[72:73], v[2:3], v[66:67] op_sel:[0,1,0] op_sel_hi:[1,1,1]
	v_pk_add_f32 v[62:63], v[62:63], v[66:67]
	s_nop 1
	v_add_f32_dpp v62, v62, v62 quad_perm:[1,0,3,2] row_mask:0xf bank_mask:0xf bound_ctrl:1
	v_add_f32_dpp v63, v63, v63 quad_perm:[1,0,3,2] row_mask:0xf bank_mask:0xf bound_ctrl:1
	s_nop 0
	v_add_f32_dpp v62, v62, v62 quad_perm:[2,3,0,1] row_mask:0xf bank_mask:0xf bound_ctrl:1
	v_add_f32_dpp v63, v63, v63 quad_perm:[2,3,0,1] row_mask:0xf bank_mask:0xf bound_ctrl:1
	s_mov_b64 exec, s[4:5]
	v_sub_f32_e32 v4, v4, v62
	v_sub_f32_e32 v5, v5, v63
	v_fma_f32 v5, v75, v62, v5
	s_mov_b64 exec, -1
.Lfs_row5:
	ds_read_b128 v[70:73], v14 offset:3264
	ds_read_b128 v[74:77], v14 offset:3328
	s_waitcnt lgkmcnt(2)
	v_pk_fma_f32 v[62:63], v[122:123], v[2:3], 0 op_sel_hi:[1,0,0]
	v_pk_fma_f32 v[66:67], v[124:125], v[2:3], 0 op_sel:[0,1,0] op_sel_hi:[1,1,0]
	v_pk_fma_f32 v[62:63], v[126:127], v[4:5], v[62:63] op_sel_hi:[1,0,1]
	v_pk_fma_f32 v[66:67], v[128:129], v[4:5], v[66:67] op_sel:[0,1,0] op_sel_hi:[1,1,1]
	v_pk_add_f32 v[62:63], v[62:63], v[66:67]
	s_nop 1
	v_add_f32_dpp v62, v62, v62 quad_perm:[1,0,3,2] row_mask:0xf bank_mask:0xf bound_ctrl:1
	v_add_f32_dpp v63, v63, v63 quad_perm:[1,0,3,2] row_mask:0xf bank_mask:0xf bound_ctrl:1
	s_nop 0
	v_add_f32_dpp v62, v62, v62 quad_perm:[2,3,0,1] row_mask:0xf bank_mask:0xf bound_ctrl:1
	v_add_f32_dpp v63, v63, v63 quad_perm:[2,3,0,1] row_mask:0xf bank_mask:0xf bound_ctrl:1
	s_mov_b64 exec, s[6:7]
	v_sub_f32_e32 v4, v4, v62
	v_sub_f32_e32 v5, v5, v63
	v_fma_f32 v5, v127, v62, v5
	s_mov_b64 exec, -1
.Lfs_row6:
	ds_read_b128 v[122:125], v14 offset:3808
	ds_read_b128 v[126:129], v14 offset:3872
	s_waitcnt lgkmcnt(2)
	v_pk_fma_f32 v[62:63], v[70:71], v[2:3], 0 op_sel_hi:[1,0,0]
	v_pk_fma_f32 v[66:67], v[72:73], v[2:3], 0 op_sel:[0,1,0] op_sel_hi:[1,1,0]
	v_pk_fma_f32 v[62:63], v[74:75], v[4:5], v[62:63] op_sel_hi:[1,0,1]
	v_pk_fma_f32 v[66:67], v[76:77], v[4:5], v[66:67] op_sel:[0,1,0] op_sel_hi:[1,1,1]
	v_pk_add_f32 v[62:63], v[62:63], v[66:67]
	s_nop 1
	v_add_f32_dpp v62, v62, v62 quad_perm:[1,0,3,2] row_mask:0xf bank_mask:0xf bound_ctrl:1
	v_add_f32_dpp v63, v63, v63 quad_perm:[1,0,3,2] row_mask:0xf bank_mask:0xf bound_ctrl:1
	s_nop 0
	v_add_f32_dpp v62, v62, v62 quad_perm:[2,3,0,1] row_mask:0xf bank_mask:0xf bound_ctrl:1
	v_add_f32_dpp v63, v63, v63 quad_perm:[2,3,0,1] row_mask:0xf bank_mask:0xf bound_ctrl:1
	s_mov_b64 exec, s[8:9]
	v_sub_f32_e32 v4, v4, v62
	v_sub_f32_e32 v5, v5, v63
	v_fma_f32 v5, v75, v62, v5
	s_mov_b64 exec, -1
; #define LAS __attribute__((address_space(3)))
;     ...
;         for (int ip = 0; ip < 32; ++ip) {
;             const int i0 = 2 * ip;
;             f32x4 rv[32];
; #pragma unroll
;             for (int jp = 0; jp <= ip; ++jp) rv[jp] = *(const LAS f32x4*)(Ad + ip * 136 + 4 * jp);
;             asm volatile("" : "+v"(lane_o) :: "memory");
;             f32x2_ a0 = {0.f, 0.f}, a1 = {0.f, 0.f}, a2 = {0.f, 0.f}, a3 = {0.f, 0.f};
; #pragma unroll
;             for (int jp = 0; jp < ip; ++jp) {
;                 const f32x2_ ta = {tr[2 * jp], tr[2 * jp]}, tb = {tr[2 * jp + 1], tr[2 * jp + 1]};
;                 const f32x2_ va = {rv[jp][0], rv[jp][1]}, vb = {rv[jp][2], rv[jp][3]};
;                 if (jp & 1) { a2 += va * ta; a3 += vb * tb; } else { a0 += va * ta; a1 += vb * tb; }
;             }
;             const f32x2_ sum = (a0 + a1) + (a2 + a3);
;             const float t0 = (lane_o == i0 ? 1.f : 0.f) - sum[0];
;             tr[i0] = t0;
;             tr[i0 + 1] = (lane_o == i0 + 1 ? 1.f : 0.f) - sum[1] - rv[ip][1] * t0;
;         }
.Lfs_row7:
	ds_read_b128 v[70:73], v14 offset:4352
	ds_read_b128 v[74:77], v14 offset:4416
	ds_read_b128 v[78:81], v14 offset:4480
	s_waitcnt lgkmcnt(3)
	v_pk_fma_f32 v[62:63], v[122:123], v[2:3], 0 op_sel_hi:[1,0,0]
	v_pk_fma_f32 v[66:67], v[124:125], v[2:3], 0 op_sel:[0,1,0] op_sel_hi:[1,1,0]
	v_pk_fma_f32 v[62:63], v[126:127], v[4:5], v[62:63] op_sel_hi:[1,0,1]
	v_pk_fma_f32 v[66:67], v[128:129], v[4:5], v[66:67] op_sel:[0,1,0] op_sel_hi:[1,1,1]
	v_pk_add_f32 v[62:63], v[62:63], v[66:67]
	s_nop 1
	v_add_f32_dpp v62, v62, v62 quad_perm:[1,0,3,2] row_mask:0xf bank_mask:0xf bound_ctrl:1
	v_add_f32_dpp v63, v63, v63 quad_perm:[1,0,3,2] row_mask:0xf bank_mask:0xf bound_ctrl:1
	s_nop 0
	v_add_f32_dpp v62, v62, v62 quad_perm:[2,3,0,1] row_mask:0xf bank_mask:0xf bound_ctrl:1
	v_add_f32_dpp v63, v63, v63 quad_perm:[2,3,0,1] row_mask:0xf bank_mask:0xf bound_ctrl:1
	s_mov_b64 exec, s[10:11]
	v_sub_f32_e32 v4, v4, v62
	v_sub_f32_e32 v5, v5, v63
	v_fma_f32 v5, v127, v62, v5
	s_mov_b64 exec, -1
.Lfs_row8:
	ds_read_b128 v[122:125], v14 offset:4896
	ds_read_b128 v[126:129], v14 offset:4960
	ds_read_b128 v[130:133], v14 offset:5024
	s_waitcnt lgkmcnt(3)
	v_pk_fma_f32 v[62:63], v[70:71], v[2:3], 0 op_sel_hi:[1,0,0]
	v_pk_fma_f32 v[66:67], v[72:73], v[2:3], 0 op_sel:[0,1,0] op_sel_hi:[1,1,0]
	v_pk_fma_f32 v[62:63], v[78:79], v[8:9], v[62:63] op_sel_hi:[1,0,1]
	v_pk_fma_f32 v[66:67], v[80:81], v[8:9], v[66:67] op_sel:[0,1,0] op_sel_hi:[1,1,1]
	v_pk_fma_f32 v[62:63], v[74:75], v[4:5], v[62:63] op_sel_hi:[1,0,1]
	v_pk_fma_f32 v[66:67], v[76:77], v[4:5], v[66:67] op_sel:[0,1,0] op_sel_hi:[1,1,1]
	v_pk_add_f32 v[62:63], v[62:63], v[66:67]
	s_nop 1
	v_add_f32_dpp v62, v62, v62 quad_perm:[1,0,3,2] row_mask:0xf bank_mask:0xf bound_ctrl:1
	v_add_f32_dpp v63, v63, v63 quad_perm:[1,0,3,2] row_mask:0xf bank_mask:0xf bound_ctrl:1
	s_nop 0
	v_add_f32_dpp v62, v62, v62 quad_perm:[2,3,0,1] row_mask:0xf bank_mask:0xf bound_ctrl:1
	v_add_f32_dpp v63, v63, v63 quad_perm:[2,3,0,1] row_mask:0xf bank_mask:0xf bound_ctrl:1
	s_mov_b64 exec, s[4:5]
	v_sub_f32_e32 v8, v8, v62
	v_sub_f32_e32 v9, v9, v63
	v_fma_f32 v9, v79, v62, v9
	s_mov_b64 exec, -1
.Lfs_row9:
	ds_read_b128 v[70:73], v14 offset:5440
	ds_read_b128 v[74:77], v14 offset:5504
	ds_read_b128 v[78:81], v14 offset:5568
	s_waitcnt lgkmcnt(3)
	v_pk_fma_f32 v[62:63], v[122:123], v[2:3], 0 op_sel_hi:[1,0,0]
	v_pk_fma_f32 v[66:67], v[124:125], v[2:3], 0 op_sel:[0,1,0] op_sel_hi:[1,1,0]
	v_pk_fma_f32 v[62:63], v[126:127], v[4:5], v[62:63] op_sel_hi:[1,0,1]
	v_pk_fma_f32 v[66:67], v[128:129], v[4:5], v[66:67] op_sel:[0,1,0] op_sel_hi:[1,1,1]
	v_pk_fma_f32 v[62:63], v[130:131], v[8:9], v[62:63] op_sel_hi:[1,0,1]
	v_pk_fma_f32 v[66:67], v[132:133], v[8:9], v[66:67] op_sel:[0,1,0] op_sel_hi:[1,1,1]
	v_pk_add_f32 v[62:63], v[62:63], v[66:67]
	s_nop 1
	v_add_f32_dpp v62, v62, v62 quad_perm:[1,0,3,2] row_mask:0xf bank_mask:0xf bound_ctrl:1
	v_add_f32_dpp v63, v63, v63 quad_perm:[1,0,3,2] row_mask:0xf bank_mask:0xf bound_ctrl:1
	s_nop 0
	v_add_f32_dpp v62, v62, v62 quad_perm:[2,3,0,1] row_mask:0xf bank_mask:0xf bound_ctrl:1
	v_add_f32_dpp v63, v63, v63 quad_perm:[2,3,0,1] row_mask:0xf bank_mask:0xf bound_ctrl:1
	s_mov_b64 exec, s[6:7]
	v_sub_f32_e32 v8, v8, v62
	v_sub_f32_e32 v9, v9, v63
	v_fma_f32 v9, v131, v62, v9
	s_mov_b64 exec, -1
.Lfs_row10:
	ds_read_b128 v[122:125], v14 offset:5984
	ds_read_b128 v[126:129], v14 offset:6048
	ds_read_b128 v[130:133], v14 offset:6112
	s_waitcnt lgkmcnt(3)
	v_pk_fma_f32 v[62:63], v[70:71], v[2:3], 0 op_sel_hi:[1,0,0]
	v_pk_fma_f32 v[66:67], v[72:73], v[2:3], 0 op_sel:[0,1,0] op_sel_hi:[1,1,0]
	v_pk_fma_f32 v[62:63], v[74:75], v[4:5], v[62:63] op_sel_hi:[1,0,1]
	v_pk_fma_f32 v[66:67], v[76:77], v[4:5], v[66:67] op_sel:[0,1,0] op_sel_hi:[1,1,1]
	v_pk_fma_f32 v[62:63], v[78:79], v[8:9], v[62:63] op_sel_hi:[1,0,1]
	v_pk_fma_f32 v[66:67], v[80:81], v[8:9], v[66:67] op_sel:[0,1,0] op_sel_hi:[1,1,1]
	v_pk_add_f32 v[62:63], v[62:63], v[66:67]
	s_nop 1
	v_add_f32_dpp v62, v62, v62 quad_perm:[1,0,3,2] row_mask:0xf bank_mask:0xf bound_ctrl:1
	v_add_f32_dpp v63, v63, v63 quad_perm:[1,0,3,2] row_mask:0xf bank_mask:0xf bound_ctrl:1
	s_nop 0
	v_add_f32_dpp v62, v62, v62 quad_perm:[2,3,0,1] row_mask:0xf bank_mask:0xf bound_ctrl:1
	v_add_f32_dpp v63, v63, v63 quad_perm:[2,3,0,1] row_mask:0xf bank_mask:0xf bound_ctrl:1
	s_mov_b64 exec, s[8:9]
	v_sub_f32_e32 v8, v8, v62
	v_sub_f32_e32 v9, v9, v63
	v_fma_f32 v9, v79, v62, v9
	s_mov_b64 exec, -1
.Lfs_row11:
	ds_read_b128 v[70:73], v14 offset:6528
	ds_read_b128 v[74:77], v14 offset:6592
	ds_read_b128 v[78:81], v14 offset:6656
	ds_read_b128 v[82:85], v14 offset:6720
	s_waitcnt lgkmcnt(4)
	v_pk_fma_f32 v[62:63], v[122:123], v[2:3], 0 op_sel_hi:[1,0,0]
	v_pk_fma_f32 v[66:67], v[124:125], v[2:3], 0 op_sel:[0,1,0] op_sel_hi:[1,1,0]
	v_pk_fma_f32 v[62:63], v[126:127], v[4:5], v[62:63] op_sel_hi:[1,0,1]
	v_pk_fma_f32 v[66:67], v[128:129], v[4:5], v[66:67] op_sel:[0,1,0] op_sel_hi:[1,1,1]
	v_pk_fma_f32 v[62:63], v[130:131], v[8:9], v[62:63] op_sel_hi:[1,0,1]
	v_pk_fma_f32 v[66:67], v[132:133], v[8:9], v[66:67] op_sel:[0,1,0] op_sel_hi:[1,1,1]
	v_pk_add_f32 v[62:63], v[62:63], v[66:67]
	s_nop 1
	v_add_f32_dpp v62, v62, v62 quad_perm:[1,0,3,2] row_mask:0xf bank_mask:0xf bound_ctrl:1
	v_add_f32_dpp v63, v63, v63 quad_perm:[1,0,3,2] row_mask:0xf bank_mask:0xf bound_ctrl:1
	s_nop 0
	v_add_f32_dpp v62, v62, v62 quad_perm:[2,3,0,1] row_mask:0xf bank_mask:0xf bound_ctrl:1
	v_add_f32_dpp v63, v63, v63 quad_perm:[2,3,0,1] row_mask:0xf bank_mask:0xf bound_ctrl:1
	s_mov_b64 exec, s[10:11]
	v_sub_f32_e32 v8, v8, v62
	v_sub_f32_e32 v9, v9, v63
	v_fma_f32 v9, v131, v62, v9
	s_mov_b64 exec, -1
; #define LAS __attribute__((address_space(3)))
;     ...
; #pragma unroll
;         for (int ip = 0; ip < 32; ++ip) {
;             const int i0 = 2 * ip;
;             f32x4 rv[32];
; #pragma unroll
;             for (int jp = 0; jp <= ip; ++jp) rv[jp] = *(const LAS f32x4*)(Ad + ip * 136 + 4 * jp);
;             asm volatile("" : "+v"(lane_o) :: "memory");
;             f32x2_ a0 = {0.f, 0.f}, a1 = {0.f, 0.f}, a2 = {0.f, 0.f}, a3 = {0.f, 0.f};
; #pragma unroll
;             for (int jp = 0; jp < ip; ++jp) {
;                 const f32x2_ ta = {tr[2 * jp], tr[2 * jp]}, tb = {tr[2 * jp + 1], tr[2 * jp + 1]};
;                 const f32x2_ va = {rv[jp][0], rv[jp][1]}, vb = {rv[jp][2], rv[jp][3]};
;                 if (jp & 1) { a2 += va * ta; a3 += vb * tb; } else { a0 += va * ta; a1 += vb * tb; }
;             }
;             const f32x2_ sum = (a0 + a1) + (a2 + a3);
;             const float t0 = (lane_o == i0 ? 1.f : 0.f) - sum[0];
;             tr[i0] = t0;
;             tr[i0 + 1] = (lane_o == i0 + 1 ? 1.f : 0.f) - sum[1] - rv[ip][1] * t0;
;         }
.Lfs_row12:
	ds_read_b128 v[122:125], v14 offset:7072
	ds_read_b128 v[126:129], v14 offset:7136
	ds_read_b128 v[130:133], v14 offset:7200
	ds_read_b128 v[38:41], v14 offset:7264
	s_waitcnt lgkmcnt(4)
	v_pk_fma_f32 v[62:63], v[70:71], v[2:3], 0 op_sel_hi:[1,0,0]
	v_pk_fma_f32 v[66:67], v[72:73], v[2:3], 0 op_sel:[0,1,0] op_sel_hi:[1,1,0]
	v_pk_fma_f32 v[62:63], v[74:75], v[4:5], v[62:63] op_sel_hi:[1,0,1]
	v_pk_fma_f32 v[66:67], v[76:77], v[4:5], v[66:67] op_sel:[0,1,0] op_sel_hi:[1,1,1]
	v_pk_fma_f32 v[62:63], v[82:83], v[10:11], v[62:63] op_sel_hi:[1,0,1]
	v_pk_fma_f32 v[66:67], v[84:85], v[10:11], v[66:67] op_sel:[0,1,0] op_sel_hi:[1,1,1]
	v_pk_fma_f32 v[62:63], v[78:79], v[8:9], v[62:63] op_sel_hi:[1,0,1]
	v_pk_fma_f32 v[66:67], v[80:81], v[8:9], v[66:67] op_sel:[0,1,0] op_sel_hi:[1,1,1]
	v_pk_add_f32 v[62:63], v[62:63], v[66:67]
	s_nop 1
	v_add_f32_dpp v62, v62, v62 quad_perm:[1,0,3,2] row_mask:0xf bank_mask:0xf bound_ctrl:1
	v_add_f32_dpp v63, v63, v63 quad_perm:[1,0,3,2] row_mask:0xf bank_mask:0xf bound_ctrl:1
	s_nop 0
	v_add_f32_dpp v62, v62, v62 quad_perm:[2,3,0,1] row_mask:0xf bank_mask:0xf bound_ctrl:1
	v_add_f32_dpp v63, v63, v63 quad_perm:[2,3,0,1] row_mask:0xf bank_mask:0xf bound_ctrl:1
	s_mov_b64 exec, s[4:5]
	v_sub_f32_e32 v10, v10, v62
	v_sub_f32_e32 v11, v11, v63
	v_fma_f32 v11, v83, v62, v11
	s_mov_b64 exec, -1
.Lfs_row13:
	ds_read_b128 v[70:73], v14 offset:7616
	ds_read_b128 v[74:77], v14 offset:7680
	ds_read_b128 v[78:81], v14 offset:7744
	ds_read_b128 v[82:85], v14 offset:7808
	s_waitcnt lgkmcnt(4)
	v_pk_fma_f32 v[62:63], v[122:123], v[2:3], 0 op_sel_hi:[1,0,0]
	v_pk_fma_f32 v[66:67], v[124:125], v[2:3], 0 op_sel:[0,1,0] op_sel_hi:[1,1,0]
	v_pk_fma_f32 v[62:63], v[126:127], v[4:5], v[62:63] op_sel_hi:[1,0,1]
	v_pk_fma_f32 v[66:67], v[128:129], v[4:5], v[66:67] op_sel:[0,1,0] op_sel_hi:[1,1,1]
	v_pk_fma_f32 v[62:63], v[130:131], v[8:9], v[62:63] op_sel_hi:[1,0,1]
	v_pk_fma_f32 v[66:67], v[132:133], v[8:9], v[66:67] op_sel:[0,1,0] op_sel_hi:[1,1,1]
	v_pk_fma_f32 v[62:63], v[38:39], v[10:11], v[62:63] op_sel_hi:[1,0,1]
	v_pk_fma_f32 v[66:67], v[40:41], v[10:11], v[66:67] op_sel:[0,1,0] op_sel_hi:[1,1,1]
	v_pk_add_f32 v[62:63], v[62:63], v[66:67]
	s_nop 1
	v_add_f32_dpp v62, v62, v62 quad_perm:[1,0,3,2] row_mask:0xf bank_mask:0xf bound_ctrl:1
	v_add_f32_dpp v63, v63, v63 quad_perm:[1,0,3,2] row_mask:0xf bank_mask:0xf bound_ctrl:1
	s_nop 0
	v_add_f32_dpp v62, v62, v62 quad_perm:[2,3,0,1] row_mask:0xf bank_mask:0xf bound_ctrl:1
	v_add_f32_dpp v63, v63, v63 quad_perm:[2,3,0,1] row_mask:0xf bank_mask:0xf bound_ctrl:1
	s_mov_b64 exec, s[6:7]
	v_sub_f32_e32 v10, v10, v62
	v_sub_f32_e32 v11, v11, v63
	v_fma_f32 v11, v39, v62, v11
	s_mov_b64 exec, -1
.Lfs_row14:
	ds_read_b128 v[122:125], v14 offset:8160
	ds_read_b128 v[126:129], v14 offset:8224
	ds_read_b128 v[130:133], v14 offset:8288
	ds_read_b128 v[38:41], v14 offset:8352
	s_waitcnt lgkmcnt(4)
	v_pk_fma_f32 v[62:63], v[70:71], v[2:3], 0 op_sel_hi:[1,0,0]
	v_pk_fma_f32 v[66:67], v[72:73], v[2:3], 0 op_sel:[0,1,0] op_sel_hi:[1,1,0]
	v_pk_fma_f32 v[62:63], v[74:75], v[4:5], v[62:63] op_sel_hi:[1,0,1]
	v_pk_fma_f32 v[66:67], v[76:77], v[4:5], v[66:67] op_sel:[0,1,0] op_sel_hi:[1,1,1]
	v_pk_fma_f32 v[62:63], v[78:79], v[8:9], v[62:63] op_sel_hi:[1,0,1]
	v_pk_fma_f32 v[66:67], v[80:81], v[8:9], v[66:67] op_sel:[0,1,0] op_sel_hi:[1,1,1]
	v_pk_fma_f32 v[62:63], v[82:83], v[10:11], v[62:63] op_sel_hi:[1,0,1]
	v_pk_fma_f32 v[66:67], v[84:85], v[10:11], v[66:67] op_sel:[0,1,0] op_sel_hi:[1,1,1]
	v_pk_add_f32 v[62:63], v[62:63], v[66:67]
	s_nop 1
	v_add_f32_dpp v62, v62, v62 quad_perm:[1,0,3,2] row_mask:0xf bank_mask:0xf bound_ctrl:1
	v_add_f32_dpp v63, v63, v63 quad_perm:[1,0,3,2] row_mask:0xf bank_mask:0xf bound_ctrl:1
	s_nop 0
	v_add_f32_dpp v62, v62, v62 quad_perm:[2,3,0,1] row_mask:0xf bank_mask:0xf bound_ctrl:1
	v_add_f32_dpp v63, v63, v63 quad_perm:[2,3,0,1] row_mask:0xf bank_mask:0xf bound_ctrl:1
	s_mov_b64 exec, s[8:9]
	v_sub_f32_e32 v10, v10, v62
	v_sub_f32_e32 v11, v11, v63
	v_fma_f32 v11, v83, v62, v11
	s_mov_b64 exec, -1
.Lfs_row15:
	ds_read_b128 v[70:73], v14 offset:8704
	ds_read_b128 v[74:77], v14 offset:8768
	ds_read_b128 v[78:81], v14 offset:8832
	ds_read_b128 v[82:85], v14 offset:8896
	ds_read_b128 v[86:89], v14 offset:8960
	s_waitcnt lgkmcnt(5)
	v_pk_fma_f32 v[62:63], v[122:123], v[2:3], 0 op_sel_hi:[1,0,0]
	v_pk_fma_f32 v[66:67], v[124:125], v[2:3], 0 op_sel:[0,1,0] op_sel_hi:[1,1,0]
	v_pk_fma_f32 v[62:63], v[126:127], v[4:5], v[62:63] op_sel_hi:[1,0,1]
	v_pk_fma_f32 v[66:67], v[128:129], v[4:5], v[66:67] op_sel:[0,1,0] op_sel_hi:[1,1,1]
	v_pk_fma_f32 v[62:63], v[130:131], v[8:9], v[62:63] op_sel_hi:[1,0,1]
	v_pk_fma_f32 v[66:67], v[132:133], v[8:9], v[66:67] op_sel:[0,1,0] op_sel_hi:[1,1,1]
	v_pk_fma_f32 v[62:63], v[38:39], v[10:11], v[62:63] op_sel_hi:[1,0,1]
	v_pk_fma_f32 v[66:67], v[40:41], v[10:11], v[66:67] op_sel:[0,1,0] op_sel_hi:[1,1,1]
	v_pk_add_f32 v[62:63], v[62:63], v[66:67]
	s_nop 1
	v_add_f32_dpp v62, v62, v62 quad_perm:[1,0,3,2] row_mask:0xf bank_mask:0xf bound_ctrl:1
	v_add_f32_dpp v63, v63, v63 quad_perm:[1,0,3,2] row_mask:0xf bank_mask:0xf bound_ctrl:1
	s_nop 0
	v_add_f32_dpp v62, v62, v62 quad_perm:[2,3,0,1] row_mask:0xf bank_mask:0xf bound_ctrl:1
	v_add_f32_dpp v63, v63, v63 quad_perm:[2,3,0,1] row_mask:0xf bank_mask:0xf bound_ctrl:1
	s_mov_b64 exec, s[10:11]
	v_sub_f32_e32 v10, v10, v62
	v_sub_f32_e32 v11, v11, v63
	v_fma_f32 v11, v39, v62, v11
	s_mov_b64 exec, -1
; #define LAS __attribute__((address_space(3)))
;     ...
; #pragma unroll
;         for (int ip = 0; ip < 32; ++ip) {
;             const int i0 = 2 * ip;
;             f32x4 rv[32];
; #pragma unroll
;             for (int jp = 0; jp <= ip; ++jp) rv[jp] = *(const LAS f32x4*)(Ad + ip * 136 + 4 * jp);
;             asm volatile("" : "+v"(lane_o) :: "memory");
;             f32x2_ a0 = {0.f, 0.f}, a1 = {0.f, 0.f}, a2 = {0.f, 0.f}, a3 = {0.f, 0.f};
; #pragma unroll
;             for (int jp = 0; jp < ip; ++jp) {
;                 const f32x2_ ta = {tr[2 * jp], tr[2 * jp]}, tb = {tr[2 * jp + 1], tr[2 * jp + 1]};
;                 const f32x2_ va = {rv[jp][0], rv[jp][1]}, vb = {rv[jp][2], rv[jp][3]};
;                 if (jp & 1) { a2 += va * ta; a3 += vb * tb; } else { a0 += va * ta; a1 += vb * tb; }
;             }
;             const f32x2_ sum = (a0 + a1) + (a2 + a3);
;             const float t0 = (lane_o == i0 ? 1.f : 0.f) - sum[0];
;             tr[i0] = t0;
;             tr[i0 + 1] = (lane_o == i0 + 1 ? 1.f : 0.f) - sum[1] - rv[ip][1] * t0;
;         }
.Lfs_row16:
	ds_read_b128 v[122:125], v14 offset:9248
	ds_read_b128 v[126:129], v14 offset:9312
	ds_read_b128 v[130:133], v14 offset:9376
	ds_read_b128 v[38:41], v14 offset:9440
	ds_read_b128 v[42:45], v14 offset:9504
	s_waitcnt lgkmcnt(5)
	v_pk_fma_f32 v[62:63], v[70:71], v[2:3], 0 op_sel_hi:[1,0,0]
	v_pk_fma_f32 v[66:67], v[72:73], v[2:3], 0 op_sel:[0,1,0] op_sel_hi:[1,1,0]
	v_pk_fma_f32 v[62:63], v[74:75], v[4:5], v[62:63] op_sel_hi:[1,0,1]
	v_pk_fma_f32 v[66:67], v[76:77], v[4:5], v[66:67] op_sel:[0,1,0] op_sel_hi:[1,1,1]
	v_pk_fma_f32 v[62:63], v[78:79], v[8:9], v[62:63] op_sel_hi:[1,0,1]
	v_pk_fma_f32 v[66:67], v[80:81], v[8:9], v[66:67] op_sel:[0,1,0] op_sel_hi:[1,1,1]
	v_pk_fma_f32 v[62:63], v[86:87], v[18:19], v[62:63] op_sel_hi:[1,0,1]
	v_pk_fma_f32 v[66:67], v[88:89], v[18:19], v[66:67] op_sel:[0,1,0] op_sel_hi:[1,1,1]
	v_pk_fma_f32 v[62:63], v[82:83], v[10:11], v[62:63] op_sel_hi:[1,0,1]
	v_pk_fma_f32 v[66:67], v[84:85], v[10:11], v[66:67] op_sel:[0,1,0] op_sel_hi:[1,1,1]
	v_pk_add_f32 v[62:63], v[62:63], v[66:67]
	s_nop 1
	v_add_f32_dpp v62, v62, v62 quad_perm:[1,0,3,2] row_mask:0xf bank_mask:0xf bound_ctrl:1
	v_add_f32_dpp v63, v63, v63 quad_perm:[1,0,3,2] row_mask:0xf bank_mask:0xf bound_ctrl:1
	s_nop 0
	v_add_f32_dpp v62, v62, v62 quad_perm:[2,3,0,1] row_mask:0xf bank_mask:0xf bound_ctrl:1
	v_add_f32_dpp v63, v63, v63 quad_perm:[2,3,0,1] row_mask:0xf bank_mask:0xf bound_ctrl:1
	s_mov_b64 exec, s[4:5]
	v_sub_f32_e32 v18, v18, v62
	v_sub_f32_e32 v19, v19, v63
	v_fma_f32 v19, v87, v62, v19
	s_mov_b64 exec, -1
.Lfs_row17:
	ds_read_b128 v[70:73], v14 offset:9792
	ds_read_b128 v[74:77], v14 offset:9856
	ds_read_b128 v[78:81], v14 offset:9920
	ds_read_b128 v[82:85], v14 offset:9984
	ds_read_b128 v[86:89], v14 offset:10048
	s_waitcnt lgkmcnt(5)
	v_pk_fma_f32 v[62:63], v[122:123], v[2:3], 0 op_sel_hi:[1,0,0]
	v_pk_fma_f32 v[66:67], v[124:125], v[2:3], 0 op_sel:[0,1,0] op_sel_hi:[1,1,0]
	v_pk_fma_f32 v[62:63], v[126:127], v[4:5], v[62:63] op_sel_hi:[1,0,1]
	v_pk_fma_f32 v[66:67], v[128:129], v[4:5], v[66:67] op_sel:[0,1,0] op_sel_hi:[1,1,1]
	v_pk_fma_f32 v[62:63], v[130:131], v[8:9], v[62:63] op_sel_hi:[1,0,1]
	v_pk_fma_f32 v[66:67], v[132:133], v[8:9], v[66:67] op_sel:[0,1,0] op_sel_hi:[1,1,1]
	v_pk_fma_f32 v[62:63], v[38:39], v[10:11], v[62:63] op_sel_hi:[1,0,1]
	v_pk_fma_f32 v[66:67], v[40:41], v[10:11], v[66:67] op_sel:[0,1,0] op_sel_hi:[1,1,1]
	v_pk_fma_f32 v[62:63], v[42:43], v[18:19], v[62:63] op_sel_hi:[1,0,1]
	v_pk_fma_f32 v[66:67], v[44:45], v[18:19], v[66:67] op_sel:[0,1,0] op_sel_hi:[1,1,1]
	v_pk_add_f32 v[62:63], v[62:63], v[66:67]
	s_nop 1
	v_add_f32_dpp v62, v62, v62 quad_perm:[1,0,3,2] row_mask:0xf bank_mask:0xf bound_ctrl:1
	v_add_f32_dpp v63, v63, v63 quad_perm:[1,0,3,2] row_mask:0xf bank_mask:0xf bound_ctrl:1
	s_nop 0
	v_add_f32_dpp v62, v62, v62 quad_perm:[2,3,0,1] row_mask:0xf bank_mask:0xf bound_ctrl:1
	v_add_f32_dpp v63, v63, v63 quad_perm:[2,3,0,1] row_mask:0xf bank_mask:0xf bound_ctrl:1
	s_mov_b64 exec, s[6:7]
	v_sub_f32_e32 v18, v18, v62
	v_sub_f32_e32 v19, v19, v63
	v_fma_f32 v19, v43, v62, v19
	s_mov_b64 exec, -1
.Lfs_row18:
	ds_read_b128 v[122:125], v14 offset:10336
	ds_read_b128 v[126:129], v14 offset:10400
	ds_read_b128 v[130:133], v14 offset:10464
	ds_read_b128 v[38:41], v14 offset:10528
	ds_read_b128 v[42:45], v14 offset:10592
	s_waitcnt lgkmcnt(5)
	v_pk_fma_f32 v[62:63], v[70:71], v[2:3], 0 op_sel_hi:[1,0,0]
	v_pk_fma_f32 v[66:67], v[72:73], v[2:3], 0 op_sel:[0,1,0] op_sel_hi:[1,1,0]
	v_pk_fma_f32 v[62:63], v[74:75], v[4:5], v[62:63] op_sel_hi:[1,0,1]
	v_pk_fma_f32 v[66:67], v[76:77], v[4:5], v[66:67] op_sel:[0,1,0] op_sel_hi:[1,1,1]
	v_pk_fma_f32 v[62:63], v[78:79], v[8:9], v[62:63] op_sel_hi:[1,0,1]
	v_pk_fma_f32 v[66:67], v[80:81], v[8:9], v[66:67] op_sel:[0,1,0] op_sel_hi:[1,1,1]
	v_pk_fma_f32 v[62:63], v[82:83], v[10:11], v[62:63] op_sel_hi:[1,0,1]
	v_pk_fma_f32 v[66:67], v[84:85], v[10:11], v[66:67] op_sel:[0,1,0] op_sel_hi:[1,1,1]
	v_pk_fma_f32 v[62:63], v[86:87], v[18:19], v[62:63] op_sel_hi:[1,0,1]
	v_pk_fma_f32 v[66:67], v[88:89], v[18:19], v[66:67] op_sel:[0,1,0] op_sel_hi:[1,1,1]
	v_pk_add_f32 v[62:63], v[62:63], v[66:67]
	s_nop 1
	v_add_f32_dpp v62, v62, v62 quad_perm:[1,0,3,2] row_mask:0xf bank_mask:0xf bound_ctrl:1
	v_add_f32_dpp v63, v63, v63 quad_perm:[1,0,3,2] row_mask:0xf bank_mask:0xf bound_ctrl:1
	s_nop 0
	v_add_f32_dpp v62, v62, v62 quad_perm:[2,3,0,1] row_mask:0xf bank_mask:0xf bound_ctrl:1
	v_add_f32_dpp v63, v63, v63 quad_perm:[2,3,0,1] row_mask:0xf bank_mask:0xf bound_ctrl:1
	s_mov_b64 exec, s[8:9]
	v_sub_f32_e32 v18, v18, v62
	v_sub_f32_e32 v19, v19, v63
	v_fma_f32 v19, v87, v62, v19
	s_mov_b64 exec, -1
.Lfs_row19:
	ds_read_b128 v[70:73], v14 offset:10880
	ds_read_b128 v[74:77], v14 offset:10944
	ds_read_b128 v[78:81], v14 offset:11008
	ds_read_b128 v[82:85], v14 offset:11072
	ds_read_b128 v[86:89], v14 offset:11136
	ds_read_b128 v[90:93], v14 offset:11200
	s_waitcnt lgkmcnt(6)
	v_pk_fma_f32 v[62:63], v[122:123], v[2:3], 0 op_sel_hi:[1,0,0]
	v_pk_fma_f32 v[66:67], v[124:125], v[2:3], 0 op_sel:[0,1,0] op_sel_hi:[1,1,0]
	v_pk_fma_f32 v[62:63], v[126:127], v[4:5], v[62:63] op_sel_hi:[1,0,1]
	v_pk_fma_f32 v[66:67], v[128:129], v[4:5], v[66:67] op_sel:[0,1,0] op_sel_hi:[1,1,1]
	v_pk_fma_f32 v[62:63], v[130:131], v[8:9], v[62:63] op_sel_hi:[1,0,1]
	v_pk_fma_f32 v[66:67], v[132:133], v[8:9], v[66:67] op_sel:[0,1,0] op_sel_hi:[1,1,1]
	v_pk_fma_f32 v[62:63], v[38:39], v[10:11], v[62:63] op_sel_hi:[1,0,1]
	v_pk_fma_f32 v[66:67], v[40:41], v[10:11], v[66:67] op_sel:[0,1,0] op_sel_hi:[1,1,1]
	v_pk_fma_f32 v[62:63], v[42:43], v[18:19], v[62:63] op_sel_hi:[1,0,1]
	v_pk_fma_f32 v[66:67], v[44:45], v[18:19], v[66:67] op_sel:[0,1,0] op_sel_hi:[1,1,1]
	v_pk_add_f32 v[62:63], v[62:63], v[66:67]
	s_nop 1
	v_add_f32_dpp v62, v62, v62 quad_perm:[1,0,3,2] row_mask:0xf bank_mask:0xf bound_ctrl:1
	v_add_f32_dpp v63, v63, v63 quad_perm:[1,0,3,2] row_mask:0xf bank_mask:0xf bound_ctrl:1
	s_nop 0
	v_add_f32_dpp v62, v62, v62 quad_perm:[2,3,0,1] row_mask:0xf bank_mask:0xf bound_ctrl:1
	v_add_f32_dpp v63, v63, v63 quad_perm:[2,3,0,1] row_mask:0xf bank_mask:0xf bound_ctrl:1
	s_mov_b64 exec, s[10:11]
	v_sub_f32_e32 v18, v18, v62
	v_sub_f32_e32 v19, v19, v63
	v_fma_f32 v19, v43, v62, v19
	s_mov_b64 exec, -1
; #define LAS __attribute__((address_space(3)))
;     ...
; #pragma unroll
;         for (int ip = 0; ip < 32; ++ip) {
;             const int i0 = 2 * ip;
;             f32x4 rv[32];
; #pragma unroll
;             for (int jp = 0; jp <= ip; ++jp) rv[jp] = *(const LAS f32x4*)(Ad + ip * 136 + 4 * jp);
;             asm volatile("" : "+v"(lane_o) :: "memory");
;             f32x2_ a0 = {0.f, 0.f}, a1 = {0.f, 0.f}, a2 = {0.f, 0.f}, a3 = {0.f, 0.f};
; #pragma unroll
;             for (int jp = 0; jp < ip; ++jp) {
;                 const f32x2_ ta = {tr[2 * jp], tr[2 * jp]}, tb = {tr[2 * jp + 1], tr[2 * jp + 1]};
;                 const f32x2_ va = {rv[jp][0], rv[jp][1]}, vb = {rv[jp][2], rv[jp][3]};
;                 if (jp & 1) { a2 += va * ta; a3 += vb * tb; } else { a0 += va * ta; a1 += vb * tb; }
;             }
;             const f32x2_ sum = (a0 + a1) + (a2 + a3);
;             const float t0 = (lane_o == i0 ? 1.f : 0.f) - sum[0];
;             tr[i0] = t0;
;             tr[i0 + 1] = (lane_o == i0 + 1 ? 1.f : 0.f) - sum[1] - rv[ip][1] * t0;
;         }
.Lfs_row20:
	ds_read_b128 v[122:125], v14 offset:11424
	ds_read_b128 v[126:129], v14 offset:11488
	ds_read_b128 v[130:133], v14 offset:11552
	ds_read_b128 v[38:41], v14 offset:11616
	ds_read_b128 v[42:45], v14 offset:11680
	ds_read_b128 v[46:49], v14 offset:11744
	s_waitcnt lgkmcnt(6)
	v_pk_fma_f32 v[62:63], v[70:71], v[2:3], 0 op_sel_hi:[1,0,0]
	v_pk_fma_f32 v[66:67], v[72:73], v[2:3], 0 op_sel:[0,1,0] op_sel_hi:[1,1,0]
	v_pk_fma_f32 v[62:63], v[74:75], v[4:5], v[62:63] op_sel_hi:[1,0,1]
	v_pk_fma_f32 v[66:67], v[76:77], v[4:5], v[66:67] op_sel:[0,1,0] op_sel_hi:[1,1,1]
	v_pk_fma_f32 v[62:63], v[78:79], v[8:9], v[62:63] op_sel_hi:[1,0,1]
	v_pk_fma_f32 v[66:67], v[80:81], v[8:9], v[66:67] op_sel:[0,1,0] op_sel_hi:[1,1,1]
	v_pk_fma_f32 v[62:63], v[82:83], v[10:11], v[62:63] op_sel_hi:[1,0,1]
	v_pk_fma_f32 v[66:67], v[84:85], v[10:11], v[66:67] op_sel:[0,1,0] op_sel_hi:[1,1,1]
	v_pk_fma_f32 v[62:63], v[90:91], v[50:51], v[62:63] op_sel_hi:[1,0,1]
	v_pk_fma_f32 v[66:67], v[92:93], v[50:51], v[66:67] op_sel:[0,1,0] op_sel_hi:[1,1,1]
	v_pk_fma_f32 v[62:63], v[86:87], v[18:19], v[62:63] op_sel_hi:[1,0,1]
	v_pk_fma_f32 v[66:67], v[88:89], v[18:19], v[66:67] op_sel:[0,1,0] op_sel_hi:[1,1,1]
	v_pk_add_f32 v[62:63], v[62:63], v[66:67]
	s_nop 1
	v_add_f32_dpp v62, v62, v62 quad_perm:[1,0,3,2] row_mask:0xf bank_mask:0xf bound_ctrl:1
	v_add_f32_dpp v63, v63, v63 quad_perm:[1,0,3,2] row_mask:0xf bank_mask:0xf bound_ctrl:1
	s_nop 0
	v_add_f32_dpp v62, v62, v62 quad_perm:[2,3,0,1] row_mask:0xf bank_mask:0xf bound_ctrl:1
	v_add_f32_dpp v63, v63, v63 quad_perm:[2,3,0,1] row_mask:0xf bank_mask:0xf bound_ctrl:1
	s_mov_b64 exec, s[4:5]
	v_sub_f32_e32 v50, v50, v62
	v_sub_f32_e32 v51, v51, v63
	v_fma_f32 v51, v91, v62, v51
	s_mov_b64 exec, -1
.Lfs_row21:
	ds_read_b128 v[70:73], v14 offset:11968
	ds_read_b128 v[74:77], v14 offset:12032
	ds_read_b128 v[78:81], v14 offset:12096
	ds_read_b128 v[82:85], v14 offset:12160
	ds_read_b128 v[86:89], v14 offset:12224
	ds_read_b128 v[90:93], v14 offset:12288
	s_waitcnt lgkmcnt(6)
	v_pk_fma_f32 v[62:63], v[122:123], v[2:3], 0 op_sel_hi:[1,0,0]
	v_pk_fma_f32 v[66:67], v[124:125], v[2:3], 0 op_sel:[0,1,0] op_sel_hi:[1,1,0]
	v_pk_fma_f32 v[62:63], v[126:127], v[4:5], v[62:63] op_sel_hi:[1,0,1]
	v_pk_fma_f32 v[66:67], v[128:129], v[4:5], v[66:67] op_sel:[0,1,0] op_sel_hi:[1,1,1]
	v_pk_fma_f32 v[62:63], v[130:131], v[8:9], v[62:63] op_sel_hi:[1,0,1]
	v_pk_fma_f32 v[66:67], v[132:133], v[8:9], v[66:67] op_sel:[0,1,0] op_sel_hi:[1,1,1]
	v_pk_fma_f32 v[62:63], v[38:39], v[10:11], v[62:63] op_sel_hi:[1,0,1]
	v_pk_fma_f32 v[66:67], v[40:41], v[10:11], v[66:67] op_sel:[0,1,0] op_sel_hi:[1,1,1]
	v_pk_fma_f32 v[62:63], v[42:43], v[18:19], v[62:63] op_sel_hi:[1,0,1]
	v_pk_fma_f32 v[66:67], v[44:45], v[18:19], v[66:67] op_sel:[0,1,0] op_sel_hi:[1,1,1]
	v_pk_fma_f32 v[62:63], v[46:47], v[50:51], v[62:63] op_sel_hi:[1,0,1]
	v_pk_fma_f32 v[66:67], v[48:49], v[50:51], v[66:67] op_sel:[0,1,0] op_sel_hi:[1,1,1]
	v_pk_add_f32 v[62:63], v[62:63], v[66:67]
	s_nop 1
	v_add_f32_dpp v62, v62, v62 quad_perm:[1,0,3,2] row_mask:0xf bank_mask:0xf bound_ctrl:1
	v_add_f32_dpp v63, v63, v63 quad_perm:[1,0,3,2] row_mask:0xf bank_mask:0xf bound_ctrl:1
	s_nop 0
	v_add_f32_dpp v62, v62, v62 quad_perm:[2,3,0,1] row_mask:0xf bank_mask:0xf bound_ctrl:1
	v_add_f32_dpp v63, v63, v63 quad_perm:[2,3,0,1] row_mask:0xf bank_mask:0xf bound_ctrl:1
	s_mov_b64 exec, s[6:7]
	v_sub_f32_e32 v50, v50, v62
	v_sub_f32_e32 v51, v51, v63
	v_fma_f32 v51, v47, v62, v51
	s_mov_b64 exec, -1
.Lfs_row22:
	ds_read_b128 v[122:125], v14 offset:12512
	ds_read_b128 v[126:129], v14 offset:12576
	ds_read_b128 v[130:133], v14 offset:12640
	ds_read_b128 v[38:41], v14 offset:12704
	ds_read_b128 v[42:45], v14 offset:12768
	ds_read_b128 v[46:49], v14 offset:12832
	s_waitcnt lgkmcnt(6)
	v_pk_fma_f32 v[62:63], v[70:71], v[2:3], 0 op_sel_hi:[1,0,0]
	v_pk_fma_f32 v[66:67], v[72:73], v[2:3], 0 op_sel:[0,1,0] op_sel_hi:[1,1,0]
	v_pk_fma_f32 v[62:63], v[74:75], v[4:5], v[62:63] op_sel_hi:[1,0,1]
	v_pk_fma_f32 v[66:67], v[76:77], v[4:5], v[66:67] op_sel:[0,1,0] op_sel_hi:[1,1,1]
	v_pk_fma_f32 v[62:63], v[78:79], v[8:9], v[62:63] op_sel_hi:[1,0,1]
	v_pk_fma_f32 v[66:67], v[80:81], v[8:9], v[66:67] op_sel:[0,1,0] op_sel_hi:[1,1,1]
	v_pk_fma_f32 v[62:63], v[82:83], v[10:11], v[62:63] op_sel_hi:[1,0,1]
	v_pk_fma_f32 v[66:67], v[84:85], v[10:11], v[66:67] op_sel:[0,1,0] op_sel_hi:[1,1,1]
	v_pk_fma_f32 v[62:63], v[86:87], v[18:19], v[62:63] op_sel_hi:[1,0,1]
	v_pk_fma_f32 v[66:67], v[88:89], v[18:19], v[66:67] op_sel:[0,1,0] op_sel_hi:[1,1,1]
	v_pk_fma_f32 v[62:63], v[90:91], v[50:51], v[62:63] op_sel_hi:[1,0,1]
	v_pk_fma_f32 v[66:67], v[92:93], v[50:51], v[66:67] op_sel:[0,1,0] op_sel_hi:[1,1,1]
	v_pk_add_f32 v[62:63], v[62:63], v[66:67]
	s_nop 1
	v_add_f32_dpp v62, v62, v62 quad_perm:[1,0,3,2] row_mask:0xf bank_mask:0xf bound_ctrl:1
	v_add_f32_dpp v63, v63, v63 quad_perm:[1,0,3,2] row_mask:0xf bank_mask:0xf bound_ctrl:1
	s_nop 0
	v_add_f32_dpp v62, v62, v62 quad_perm:[2,3,0,1] row_mask:0xf bank_mask:0xf bound_ctrl:1
	v_add_f32_dpp v63, v63, v63 quad_perm:[2,3,0,1] row_mask:0xf bank_mask:0xf bound_ctrl:1
	s_mov_b64 exec, s[8:9]
	v_sub_f32_e32 v50, v50, v62
	v_sub_f32_e32 v51, v51, v63
	v_fma_f32 v51, v91, v62, v51
	s_mov_b64 exec, -1
; #define LAS __attribute__((address_space(3)))
;     ...
; #pragma unroll
;         for (int ip = 0; ip < 32; ++ip) {
;             const int i0 = 2 * ip;
;             f32x4 rv[32];
; #pragma unroll
;             for (int jp = 0; jp <= ip; ++jp) rv[jp] = *(const LAS f32x4*)(Ad + ip * 136 + 4 * jp);
;             asm volatile("" : "+v"(lane_o) :: "memory");
;             f32x2_ a0 = {0.f, 0.f}, a1 = {0.f, 0.f}, a2 = {0.f, 0.f}, a3 = {0.f, 0.f};
; #pragma unroll
;             for (int jp = 0; jp < ip; ++jp) {
;                 const f32x2_ ta = {tr[2 * jp], tr[2 * jp]}, tb = {tr[2 * jp + 1], tr[2 * jp + 1]};
;                 const f32x2_ va = {rv[jp][0], rv[jp][1]}, vb = {rv[jp][2], rv[jp][3]};
;                 if (jp & 1) { a2 += va * ta; a3 += vb * tb; } else { a0 += va * ta; a1 += vb * tb; }
;             }
;             const f32x2_ sum = (a0 + a1) + (a2 + a3);
;             const float t0 = (lane_o == i0 ? 1.f : 0.f) - sum[0];
;             tr[i0] = t0;
;             tr[i0 + 1] = (lane_o == i0 + 1 ? 1.f : 0.f) - sum[1] - rv[ip][1] * t0;
;         }
.Lfs_row23:
	ds_read_b128 v[70:73], v14 offset:13056
	ds_read_b128 v[74:77], v14 offset:13120
	ds_read_b128 v[78:81], v14 offset:13184
	ds_read_b128 v[82:85], v14 offset:13248
	ds_read_b128 v[86:89], v14 offset:13312
	ds_read_b128 v[90:93], v14 offset:13376
	ds_read_b128 v[94:97], v14 offset:13440
	s_waitcnt lgkmcnt(7)
	v_pk_fma_f32 v[62:63], v[122:123], v[2:3], 0 op_sel_hi:[1,0,0]
	v_pk_fma_f32 v[66:67], v[124:125], v[2:3], 0 op_sel:[0,1,0] op_sel_hi:[1,1,0]
	v_pk_fma_f32 v[62:63], v[126:127], v[4:5], v[62:63] op_sel_hi:[1,0,1]
	v_pk_fma_f32 v[66:67], v[128:129], v[4:5], v[66:67] op_sel:[0,1,0] op_sel_hi:[1,1,1]
	v_pk_fma_f32 v[62:63], v[130:131], v[8:9], v[62:63] op_sel_hi:[1,0,1]
	v_pk_fma_f32 v[66:67], v[132:133], v[8:9], v[66:67] op_sel:[0,1,0] op_sel_hi:[1,1,1]
	v_pk_fma_f32 v[62:63], v[38:39], v[10:11], v[62:63] op_sel_hi:[1,0,1]
	v_pk_fma_f32 v[66:67], v[40:41], v[10:11], v[66:67] op_sel:[0,1,0] op_sel_hi:[1,1,1]
	v_pk_fma_f32 v[62:63], v[42:43], v[18:19], v[62:63] op_sel_hi:[1,0,1]
	v_pk_fma_f32 v[66:67], v[44:45], v[18:19], v[66:67] op_sel:[0,1,0] op_sel_hi:[1,1,1]
	v_pk_fma_f32 v[62:63], v[46:47], v[50:51], v[62:63] op_sel_hi:[1,0,1]
	v_pk_fma_f32 v[66:67], v[48:49], v[50:51], v[66:67] op_sel:[0,1,0] op_sel_hi:[1,1,1]
	v_pk_add_f32 v[62:63], v[62:63], v[66:67]
	s_nop 1
	v_add_f32_dpp v62, v62, v62 quad_perm:[1,0,3,2] row_mask:0xf bank_mask:0xf bound_ctrl:1
	v_add_f32_dpp v63, v63, v63 quad_perm:[1,0,3,2] row_mask:0xf bank_mask:0xf bound_ctrl:1
	s_nop 0
	v_add_f32_dpp v62, v62, v62 quad_perm:[2,3,0,1] row_mask:0xf bank_mask:0xf bound_ctrl:1
	v_add_f32_dpp v63, v63, v63 quad_perm:[2,3,0,1] row_mask:0xf bank_mask:0xf bound_ctrl:1
	s_mov_b64 exec, s[10:11]
	v_sub_f32_e32 v50, v50, v62
	v_sub_f32_e32 v51, v51, v63
	v_fma_f32 v51, v47, v62, v51
	s_mov_b64 exec, -1
.Lfs_row24:
	ds_read_b128 v[122:125], v14 offset:13600
	ds_read_b128 v[126:129], v14 offset:13664
	ds_read_b128 v[130:133], v14 offset:13728
	ds_read_b128 v[38:41], v14 offset:13792
	ds_read_b128 v[42:45], v14 offset:13856
	ds_read_b128 v[46:49], v14 offset:13920
	ds_read_b128 v[102:105], v14 offset:13984
	s_waitcnt lgkmcnt(7)
	v_pk_fma_f32 v[62:63], v[70:71], v[2:3], 0 op_sel_hi:[1,0,0]
	v_pk_fma_f32 v[66:67], v[72:73], v[2:3], 0 op_sel:[0,1,0] op_sel_hi:[1,1,0]
	v_pk_fma_f32 v[62:63], v[74:75], v[4:5], v[62:63] op_sel_hi:[1,0,1]
	v_pk_fma_f32 v[66:67], v[76:77], v[4:5], v[66:67] op_sel:[0,1,0] op_sel_hi:[1,1,1]
	v_pk_fma_f32 v[62:63], v[78:79], v[8:9], v[62:63] op_sel_hi:[1,0,1]
	v_pk_fma_f32 v[66:67], v[80:81], v[8:9], v[66:67] op_sel:[0,1,0] op_sel_hi:[1,1,1]
	v_pk_fma_f32 v[62:63], v[82:83], v[10:11], v[62:63] op_sel_hi:[1,0,1]
	v_pk_fma_f32 v[66:67], v[84:85], v[10:11], v[66:67] op_sel:[0,1,0] op_sel_hi:[1,1,1]
	v_pk_fma_f32 v[62:63], v[86:87], v[18:19], v[62:63] op_sel_hi:[1,0,1]
	v_pk_fma_f32 v[66:67], v[88:89], v[18:19], v[66:67] op_sel:[0,1,0] op_sel_hi:[1,1,1]
	v_pk_fma_f32 v[62:63], v[94:95], v[54:55], v[62:63] op_sel_hi:[1,0,1]
	v_pk_fma_f32 v[66:67], v[96:97], v[54:55], v[66:67] op_sel:[0,1,0] op_sel_hi:[1,1,1]
	v_pk_fma_f32 v[62:63], v[90:91], v[50:51], v[62:63] op_sel_hi:[1,0,1]
	v_pk_fma_f32 v[66:67], v[92:93], v[50:51], v[66:67] op_sel:[0,1,0] op_sel_hi:[1,1,1]
	v_pk_add_f32 v[62:63], v[62:63], v[66:67]
	s_nop 1
	v_add_f32_dpp v62, v62, v62 quad_perm:[1,0,3,2] row_mask:0xf bank_mask:0xf bound_ctrl:1
	v_add_f32_dpp v63, v63, v63 quad_perm:[1,0,3,2] row_mask:0xf bank_mask:0xf bound_ctrl:1
	s_nop 0
	v_add_f32_dpp v62, v62, v62 quad_perm:[2,3,0,1] row_mask:0xf bank_mask:0xf bound_ctrl:1
	v_add_f32_dpp v63, v63, v63 quad_perm:[2,3,0,1] row_mask:0xf bank_mask:0xf bound_ctrl:1
	s_mov_b64 exec, s[4:5]
	v_sub_f32_e32 v54, v54, v62
	v_sub_f32_e32 v55, v55, v63
	v_fma_f32 v55, v95, v62, v55
	s_mov_b64 exec, -1
.Lfs_row25:
	ds_read_b128 v[70:73], v14 offset:14144
	ds_read_b128 v[74:77], v14 offset:14208
	ds_read_b128 v[78:81], v14 offset:14272
	ds_read_b128 v[82:85], v14 offset:14336
	ds_read_b128 v[86:89], v14 offset:14400
	ds_read_b128 v[90:93], v14 offset:14464
	ds_read_b128 v[94:97], v14 offset:14528
	s_waitcnt lgkmcnt(7)
	v_pk_fma_f32 v[62:63], v[122:123], v[2:3], 0 op_sel_hi:[1,0,0]
	v_pk_fma_f32 v[66:67], v[124:125], v[2:3], 0 op_sel:[0,1,0] op_sel_hi:[1,1,0]
	v_pk_fma_f32 v[62:63], v[126:127], v[4:5], v[62:63] op_sel_hi:[1,0,1]
	v_pk_fma_f32 v[66:67], v[128:129], v[4:5], v[66:67] op_sel:[0,1,0] op_sel_hi:[1,1,1]
	v_pk_fma_f32 v[62:63], v[130:131], v[8:9], v[62:63] op_sel_hi:[1,0,1]
	v_pk_fma_f32 v[66:67], v[132:133], v[8:9], v[66:67] op_sel:[0,1,0] op_sel_hi:[1,1,1]
	v_pk_fma_f32 v[62:63], v[38:39], v[10:11], v[62:63] op_sel_hi:[1,0,1]
	v_pk_fma_f32 v[66:67], v[40:41], v[10:11], v[66:67] op_sel:[0,1,0] op_sel_hi:[1,1,1]
	v_pk_fma_f32 v[62:63], v[42:43], v[18:19], v[62:63] op_sel_hi:[1,0,1]
	v_pk_fma_f32 v[66:67], v[44:45], v[18:19], v[66:67] op_sel:[0,1,0] op_sel_hi:[1,1,1]
	v_pk_fma_f32 v[62:63], v[46:47], v[50:51], v[62:63] op_sel_hi:[1,0,1]
	v_pk_fma_f32 v[66:67], v[48:49], v[50:51], v[66:67] op_sel:[0,1,0] op_sel_hi:[1,1,1]
	v_pk_fma_f32 v[62:63], v[102:103], v[54:55], v[62:63] op_sel_hi:[1,0,1]
	v_pk_fma_f32 v[66:67], v[104:105], v[54:55], v[66:67] op_sel:[0,1,0] op_sel_hi:[1,1,1]
	v_pk_add_f32 v[62:63], v[62:63], v[66:67]
	s_nop 1
	v_add_f32_dpp v62, v62, v62 quad_perm:[1,0,3,2] row_mask:0xf bank_mask:0xf bound_ctrl:1
	v_add_f32_dpp v63, v63, v63 quad_perm:[1,0,3,2] row_mask:0xf bank_mask:0xf bound_ctrl:1
	s_nop 0
	v_add_f32_dpp v62, v62, v62 quad_perm:[2,3,0,1] row_mask:0xf bank_mask:0xf bound_ctrl:1
	v_add_f32_dpp v63, v63, v63 quad_perm:[2,3,0,1] row_mask:0xf bank_mask:0xf bound_ctrl:1
	s_mov_b64 exec, s[6:7]
	v_sub_f32_e32 v54, v54, v62
	v_sub_f32_e32 v55, v55, v63
	v_fma_f32 v55, v103, v62, v55
	s_mov_b64 exec, -1
; #define LAS __attribute__((address_space(3)))
;     ...
; #pragma unroll
;         for (int ip = 0; ip < 32; ++ip) {
;             const int i0 = 2 * ip;
;             f32x4 rv[32];
; #pragma unroll
;             for (int jp = 0; jp <= ip; ++jp) rv[jp] = *(const LAS f32x4*)(Ad + ip * 136 + 4 * jp);
;             asm volatile("" : "+v"(lane_o) :: "memory");
;             f32x2_ a0 = {0.f, 0.f}, a1 = {0.f, 0.f}, a2 = {0.f, 0.f}, a3 = {0.f, 0.f};
; #pragma unroll
;             for (int jp = 0; jp < ip; ++jp) {
;                 const f32x2_ ta = {tr[2 * jp], tr[2 * jp]}, tb = {tr[2 * jp + 1], tr[2 * jp + 1]};
;                 const f32x2_ va = {rv[jp][0], rv[jp][1]}, vb = {rv[jp][2], rv[jp][3]};
;                 if (jp & 1) { a2 += va * ta; a3 += vb * tb; } else { a0 += va * ta; a1 += vb * tb; }
;             }
;             const f32x2_ sum = (a0 + a1) + (a2 + a3);
;             const float t0 = (lane_o == i0 ? 1.f : 0.f) - sum[0];
;             tr[i0] = t0;
;             tr[i0 + 1] = (lane_o == i0 + 1 ? 1.f : 0.f) - sum[1] - rv[ip][1] * t0;
;         }
.Lfs_row26:
	ds_read_b128 v[122:125], v14 offset:14688
	ds_read_b128 v[126:129], v14 offset:14752
	ds_read_b128 v[130:133], v14 offset:14816
	ds_read_b128 v[38:41], v14 offset:14880
	ds_read_b128 v[42:45], v14 offset:14944
	ds_read_b128 v[46:49], v14 offset:15008
	ds_read_b128 v[102:105], v14 offset:15072
	s_waitcnt lgkmcnt(7)
	v_pk_fma_f32 v[62:63], v[70:71], v[2:3], 0 op_sel_hi:[1,0,0]
	v_pk_fma_f32 v[66:67], v[72:73], v[2:3], 0 op_sel:[0,1,0] op_sel_hi:[1,1,0]
	v_pk_fma_f32 v[62:63], v[74:75], v[4:5], v[62:63] op_sel_hi:[1,0,1]
	v_pk_fma_f32 v[66:67], v[76:77], v[4:5], v[66:67] op_sel:[0,1,0] op_sel_hi:[1,1,1]
	v_pk_fma_f32 v[62:63], v[78:79], v[8:9], v[62:63] op_sel_hi:[1,0,1]
	v_pk_fma_f32 v[66:67], v[80:81], v[8:9], v[66:67] op_sel:[0,1,0] op_sel_hi:[1,1,1]
	v_pk_fma_f32 v[62:63], v[82:83], v[10:11], v[62:63] op_sel_hi:[1,0,1]
	v_pk_fma_f32 v[66:67], v[84:85], v[10:11], v[66:67] op_sel:[0,1,0] op_sel_hi:[1,1,1]
	v_pk_fma_f32 v[62:63], v[86:87], v[18:19], v[62:63] op_sel_hi:[1,0,1]
	v_pk_fma_f32 v[66:67], v[88:89], v[18:19], v[66:67] op_sel:[0,1,0] op_sel_hi:[1,1,1]
	v_pk_fma_f32 v[62:63], v[90:91], v[50:51], v[62:63] op_sel_hi:[1,0,1]
	v_pk_fma_f32 v[66:67], v[92:93], v[50:51], v[66:67] op_sel:[0,1,0] op_sel_hi:[1,1,1]
	v_pk_fma_f32 v[62:63], v[94:95], v[54:55], v[62:63] op_sel_hi:[1,0,1]
	v_pk_fma_f32 v[66:67], v[96:97], v[54:55], v[66:67] op_sel:[0,1,0] op_sel_hi:[1,1,1]
	v_pk_add_f32 v[62:63], v[62:63], v[66:67]
	s_nop 1
	v_add_f32_dpp v62, v62, v62 quad_perm:[1,0,3,2] row_mask:0xf bank_mask:0xf bound_ctrl:1
	v_add_f32_dpp v63, v63, v63 quad_perm:[1,0,3,2] row_mask:0xf bank_mask:0xf bound_ctrl:1
	s_nop 0
	v_add_f32_dpp v62, v62, v62 quad_perm:[2,3,0,1] row_mask:0xf bank_mask:0xf bound_ctrl:1
	v_add_f32_dpp v63, v63, v63 quad_perm:[2,3,0,1] row_mask:0xf bank_mask:0xf bound_ctrl:1
	s_mov_b64 exec, s[8:9]
	v_sub_f32_e32 v54, v54, v62
	v_sub_f32_e32 v55, v55, v63
	v_fma_f32 v55, v95, v62, v55
	s_mov_b64 exec, -1
.Lfs_row27:
	ds_read_b128 v[70:73], v14 offset:15232
	ds_read_b128 v[74:77], v14 offset:15296
	ds_read_b128 v[78:81], v14 offset:15360
	ds_read_b128 v[82:85], v14 offset:15424
	ds_read_b128 v[86:89], v14 offset:15488
	ds_read_b128 v[90:93], v14 offset:15552
	ds_read_b128 v[94:97], v14 offset:15616
	ds_read_b128 v[98:101], v14 offset:15680
	s_waitcnt lgkmcnt(8)
	v_pk_fma_f32 v[62:63], v[122:123], v[2:3], 0 op_sel_hi:[1,0,0]
	v_pk_fma_f32 v[66:67], v[124:125], v[2:3], 0 op_sel:[0,1,0] op_sel_hi:[1,1,0]
	v_pk_fma_f32 v[62:63], v[126:127], v[4:5], v[62:63] op_sel_hi:[1,0,1]
	v_pk_fma_f32 v[66:67], v[128:129], v[4:5], v[66:67] op_sel:[0,1,0] op_sel_hi:[1,1,1]
	v_pk_fma_f32 v[62:63], v[130:131], v[8:9], v[62:63] op_sel_hi:[1,0,1]
	v_pk_fma_f32 v[66:67], v[132:133], v[8:9], v[66:67] op_sel:[0,1,0] op_sel_hi:[1,1,1]
	v_pk_fma_f32 v[62:63], v[38:39], v[10:11], v[62:63] op_sel_hi:[1,0,1]
	v_pk_fma_f32 v[66:67], v[40:41], v[10:11], v[66:67] op_sel:[0,1,0] op_sel_hi:[1,1,1]
	v_pk_fma_f32 v[62:63], v[42:43], v[18:19], v[62:63] op_sel_hi:[1,0,1]
	v_pk_fma_f32 v[66:67], v[44:45], v[18:19], v[66:67] op_sel:[0,1,0] op_sel_hi:[1,1,1]
	v_pk_fma_f32 v[62:63], v[46:47], v[50:51], v[62:63] op_sel_hi:[1,0,1]
	v_pk_fma_f32 v[66:67], v[48:49], v[50:51], v[66:67] op_sel:[0,1,0] op_sel_hi:[1,1,1]
	v_pk_fma_f32 v[62:63], v[102:103], v[54:55], v[62:63] op_sel_hi:[1,0,1]
	v_pk_fma_f32 v[66:67], v[104:105], v[54:55], v[66:67] op_sel:[0,1,0] op_sel_hi:[1,1,1]
	v_pk_add_f32 v[62:63], v[62:63], v[66:67]
	s_nop 1
	v_add_f32_dpp v62, v62, v62 quad_perm:[1,0,3,2] row_mask:0xf bank_mask:0xf bound_ctrl:1
	v_add_f32_dpp v63, v63, v63 quad_perm:[1,0,3,2] row_mask:0xf bank_mask:0xf bound_ctrl:1
	s_nop 0
	v_add_f32_dpp v62, v62, v62 quad_perm:[2,3,0,1] row_mask:0xf bank_mask:0xf bound_ctrl:1
	v_add_f32_dpp v63, v63, v63 quad_perm:[2,3,0,1] row_mask:0xf bank_mask:0xf bound_ctrl:1
	s_mov_b64 exec, s[10:11]
	v_sub_f32_e32 v54, v54, v62
	v_sub_f32_e32 v55, v55, v63
	v_fma_f32 v55, v103, v62, v55
	s_mov_b64 exec, -1
.Lfs_row28:
	ds_read_b128 v[122:125], v14 offset:15776
	ds_read_b128 v[126:129], v14 offset:15840
	ds_read_b128 v[130:133], v14 offset:15904
	ds_read_b128 v[38:41], v14 offset:15968
	ds_read_b128 v[42:45], v14 offset:16032
	ds_read_b128 v[46:49], v14 offset:16096
	ds_read_b128 v[102:105], v14 offset:16160
	ds_read_b128 v[242:245], v14 offset:16224
	s_waitcnt lgkmcnt(8)
	v_pk_fma_f32 v[62:63], v[70:71], v[2:3], 0 op_sel_hi:[1,0,0]
	v_pk_fma_f32 v[66:67], v[72:73], v[2:3], 0 op_sel:[0,1,0] op_sel_hi:[1,1,0]
	v_pk_fma_f32 v[62:63], v[74:75], v[4:5], v[62:63] op_sel_hi:[1,0,1]
	v_pk_fma_f32 v[66:67], v[76:77], v[4:5], v[66:67] op_sel:[0,1,0] op_sel_hi:[1,1,1]
	v_pk_fma_f32 v[62:63], v[78:79], v[8:9], v[62:63] op_sel_hi:[1,0,1]
	v_pk_fma_f32 v[66:67], v[80:81], v[8:9], v[66:67] op_sel:[0,1,0] op_sel_hi:[1,1,1]
	v_pk_fma_f32 v[62:63], v[82:83], v[10:11], v[62:63] op_sel_hi:[1,0,1]
	v_pk_fma_f32 v[66:67], v[84:85], v[10:11], v[66:67] op_sel:[0,1,0] op_sel_hi:[1,1,1]
	v_pk_fma_f32 v[62:63], v[86:87], v[18:19], v[62:63] op_sel_hi:[1,0,1]
	v_pk_fma_f32 v[66:67], v[88:89], v[18:19], v[66:67] op_sel:[0,1,0] op_sel_hi:[1,1,1]
	v_pk_fma_f32 v[62:63], v[90:91], v[50:51], v[62:63] op_sel_hi:[1,0,1]
	v_pk_fma_f32 v[66:67], v[92:93], v[50:51], v[66:67] op_sel:[0,1,0] op_sel_hi:[1,1,1]
	v_pk_fma_f32 v[62:63], v[98:99], v[58:59], v[62:63] op_sel_hi:[1,0,1]
	v_pk_fma_f32 v[66:67], v[100:101], v[58:59], v[66:67] op_sel:[0,1,0] op_sel_hi:[1,1,1]
	v_pk_fma_f32 v[62:63], v[94:95], v[54:55], v[62:63] op_sel_hi:[1,0,1]
	v_pk_fma_f32 v[66:67], v[96:97], v[54:55], v[66:67] op_sel:[0,1,0] op_sel_hi:[1,1,1]
	v_pk_add_f32 v[62:63], v[62:63], v[66:67]
	s_nop 1
	v_add_f32_dpp v62, v62, v62 quad_perm:[1,0,3,2] row_mask:0xf bank_mask:0xf bound_ctrl:1
	v_add_f32_dpp v63, v63, v63 quad_perm:[1,0,3,2] row_mask:0xf bank_mask:0xf bound_ctrl:1
	s_nop 0
	v_add_f32_dpp v62, v62, v62 quad_perm:[2,3,0,1] row_mask:0xf bank_mask:0xf bound_ctrl:1
	v_add_f32_dpp v63, v63, v63 quad_perm:[2,3,0,1] row_mask:0xf bank_mask:0xf bound_ctrl:1
	s_mov_b64 exec, s[4:5]
	v_sub_f32_e32 v58, v58, v62
	v_sub_f32_e32 v59, v59, v63
	v_fma_f32 v59, v99, v62, v59
	s_mov_b64 exec, -1
; #define LAS __attribute__((address_space(3)))
;     ...
; #pragma unroll
;         for (int ip = 0; ip < 32; ++ip) {
;             const int i0 = 2 * ip;
;             f32x4 rv[32];
; #pragma unroll
;             for (int jp = 0; jp <= ip; ++jp) rv[jp] = *(const LAS f32x4*)(Ad + ip * 136 + 4 * jp);
;             asm volatile("" : "+v"(lane_o) :: "memory");
;             f32x2_ a0 = {0.f, 0.f}, a1 = {0.f, 0.f}, a2 = {0.f, 0.f}, a3 = {0.f, 0.f};
; #pragma unroll
;             for (int jp = 0; jp < ip; ++jp) {
;                 const f32x2_ ta = {tr[2 * jp], tr[2 * jp]}, tb = {tr[2 * jp + 1], tr[2 * jp + 1]};
;                 const f32x2_ va = {rv[jp][0], rv[jp][1]}, vb = {rv[jp][2], rv[jp][3]};
;                 if (jp & 1) { a2 += va * ta; a3 += vb * tb; } else { a0 += va * ta; a1 += vb * tb; }
;             }
;             const f32x2_ sum = (a0 + a1) + (a2 + a3);
;             const float t0 = (lane_o == i0 ? 1.f : 0.f) - sum[0];
;             tr[i0] = t0;
;             tr[i0 + 1] = (lane_o == i0 + 1 ? 1.f : 0.f) - sum[1] - rv[ip][1] * t0;
;         }
.Lfs_row29:
	ds_read_b128 v[70:73], v14 offset:16320
	ds_read_b128 v[74:77], v14 offset:16384
	ds_read_b128 v[78:81], v14 offset:16448
	ds_read_b128 v[82:85], v14 offset:16512
	ds_read_b128 v[86:89], v14 offset:16576
	ds_read_b128 v[90:93], v14 offset:16640
	ds_read_b128 v[94:97], v14 offset:16704
	ds_read_b128 v[98:101], v14 offset:16768
	s_waitcnt lgkmcnt(8)
	v_pk_fma_f32 v[62:63], v[122:123], v[2:3], 0 op_sel_hi:[1,0,0]
	v_pk_fma_f32 v[66:67], v[124:125], v[2:3], 0 op_sel:[0,1,0] op_sel_hi:[1,1,0]
	v_pk_fma_f32 v[62:63], v[126:127], v[4:5], v[62:63] op_sel_hi:[1,0,1]
	v_pk_fma_f32 v[66:67], v[128:129], v[4:5], v[66:67] op_sel:[0,1,0] op_sel_hi:[1,1,1]
	v_pk_fma_f32 v[62:63], v[130:131], v[8:9], v[62:63] op_sel_hi:[1,0,1]
	v_pk_fma_f32 v[66:67], v[132:133], v[8:9], v[66:67] op_sel:[0,1,0] op_sel_hi:[1,1,1]
	v_pk_fma_f32 v[62:63], v[38:39], v[10:11], v[62:63] op_sel_hi:[1,0,1]
	v_pk_fma_f32 v[66:67], v[40:41], v[10:11], v[66:67] op_sel:[0,1,0] op_sel_hi:[1,1,1]
	v_pk_fma_f32 v[62:63], v[42:43], v[18:19], v[62:63] op_sel_hi:[1,0,1]
	v_pk_fma_f32 v[66:67], v[44:45], v[18:19], v[66:67] op_sel:[0,1,0] op_sel_hi:[1,1,1]
	v_pk_fma_f32 v[62:63], v[46:47], v[50:51], v[62:63] op_sel_hi:[1,0,1]
	v_pk_fma_f32 v[66:67], v[48:49], v[50:51], v[66:67] op_sel:[0,1,0] op_sel_hi:[1,1,1]
	v_pk_fma_f32 v[62:63], v[102:103], v[54:55], v[62:63] op_sel_hi:[1,0,1]
	v_pk_fma_f32 v[66:67], v[104:105], v[54:55], v[66:67] op_sel:[0,1,0] op_sel_hi:[1,1,1]
	v_pk_fma_f32 v[62:63], v[242:243], v[58:59], v[62:63] op_sel_hi:[1,0,1]
	v_pk_fma_f32 v[66:67], v[244:245], v[58:59], v[66:67] op_sel:[0,1,0] op_sel_hi:[1,1,1]
	v_pk_add_f32 v[62:63], v[62:63], v[66:67]
	s_nop 1
	v_add_f32_dpp v62, v62, v62 quad_perm:[1,0,3,2] row_mask:0xf bank_mask:0xf bound_ctrl:1
	v_add_f32_dpp v63, v63, v63 quad_perm:[1,0,3,2] row_mask:0xf bank_mask:0xf bound_ctrl:1
	s_nop 0
	v_add_f32_dpp v62, v62, v62 quad_perm:[2,3,0,1] row_mask:0xf bank_mask:0xf bound_ctrl:1
	v_add_f32_dpp v63, v63, v63 quad_perm:[2,3,0,1] row_mask:0xf bank_mask:0xf bound_ctrl:1
	s_mov_b64 exec, s[6:7]
	v_sub_f32_e32 v58, v58, v62
	v_sub_f32_e32 v59, v59, v63
	v_fma_f32 v59, v243, v62, v59
	s_mov_b64 exec, -1
.Lfs_row30:
	ds_read_b128 v[122:125], v14 offset:16864
	ds_read_b128 v[126:129], v14 offset:16928
	ds_read_b128 v[130:133], v14 offset:16992
	ds_read_b128 v[38:41], v14 offset:17056
	ds_read_b128 v[42:45], v14 offset:17120
	ds_read_b128 v[46:49], v14 offset:17184
	ds_read_b128 v[102:105], v14 offset:17248
	ds_read_b128 v[242:245], v14 offset:17312
	s_waitcnt lgkmcnt(8)
	v_pk_fma_f32 v[62:63], v[70:71], v[2:3], 0 op_sel_hi:[1,0,0]
	v_pk_fma_f32 v[66:67], v[72:73], v[2:3], 0 op_sel:[0,1,0] op_sel_hi:[1,1,0]
	v_pk_fma_f32 v[62:63], v[74:75], v[4:5], v[62:63] op_sel_hi:[1,0,1]
	v_pk_fma_f32 v[66:67], v[76:77], v[4:5], v[66:67] op_sel:[0,1,0] op_sel_hi:[1,1,1]
	v_pk_fma_f32 v[62:63], v[78:79], v[8:9], v[62:63] op_sel_hi:[1,0,1]
	v_pk_fma_f32 v[66:67], v[80:81], v[8:9], v[66:67] op_sel:[0,1,0] op_sel_hi:[1,1,1]
	v_pk_fma_f32 v[62:63], v[82:83], v[10:11], v[62:63] op_sel_hi:[1,0,1]
	v_pk_fma_f32 v[66:67], v[84:85], v[10:11], v[66:67] op_sel:[0,1,0] op_sel_hi:[1,1,1]
	v_pk_fma_f32 v[62:63], v[86:87], v[18:19], v[62:63] op_sel_hi:[1,0,1]
	v_pk_fma_f32 v[66:67], v[88:89], v[18:19], v[66:67] op_sel:[0,1,0] op_sel_hi:[1,1,1]
	v_pk_fma_f32 v[62:63], v[90:91], v[50:51], v[62:63] op_sel_hi:[1,0,1]
	v_pk_fma_f32 v[66:67], v[92:93], v[50:51], v[66:67] op_sel:[0,1,0] op_sel_hi:[1,1,1]
	v_pk_fma_f32 v[62:63], v[94:95], v[54:55], v[62:63] op_sel_hi:[1,0,1]
	v_pk_fma_f32 v[66:67], v[96:97], v[54:55], v[66:67] op_sel:[0,1,0] op_sel_hi:[1,1,1]
	v_pk_fma_f32 v[62:63], v[98:99], v[58:59], v[62:63] op_sel_hi:[1,0,1]
	v_pk_fma_f32 v[66:67], v[100:101], v[58:59], v[66:67] op_sel:[0,1,0] op_sel_hi:[1,1,1]
	v_pk_add_f32 v[62:63], v[62:63], v[66:67]
	s_nop 1
	v_add_f32_dpp v62, v62, v62 quad_perm:[1,0,3,2] row_mask:0xf bank_mask:0xf bound_ctrl:1
	v_add_f32_dpp v63, v63, v63 quad_perm:[1,0,3,2] row_mask:0xf bank_mask:0xf bound_ctrl:1
	s_nop 0
	v_add_f32_dpp v62, v62, v62 quad_perm:[2,3,0,1] row_mask:0xf bank_mask:0xf bound_ctrl:1
	v_add_f32_dpp v63, v63, v63 quad_perm:[2,3,0,1] row_mask:0xf bank_mask:0xf bound_ctrl:1
	s_mov_b64 exec, s[8:9]
	v_sub_f32_e32 v58, v58, v62
	v_sub_f32_e32 v59, v59, v63
	v_fma_f32 v59, v99, v62, v59
	s_mov_b64 exec, -1
; #define LAS __attribute__((address_space(3)))
; __device__ __forceinline__ unsigned f2bf(float f) { return pk2(f, 0.f) & 0xffffu; }
; __device__ __forceinline__ float fexp(float x) { return __builtin_amdgcn_exp2f(x * 1.4426950408889634f); }
;     ...
; #pragma unroll
;         for (int ip = 0; ip < 32; ++ip) {
;             const int i0 = 2 * ip;
;             f32x4 rv[32];
; #pragma unroll
;             for (int jp = 0; jp <= ip; ++jp) rv[jp] = *(const LAS f32x4*)(Ad + ip * 136 + 4 * jp);
;             asm volatile("" : "+v"(lane_o) :: "memory");
;             f32x2_ a0 = {0.f, 0.f}, a1 = {0.f, 0.f}, a2 = {0.f, 0.f}, a3 = {0.f, 0.f};
; #pragma unroll
;             for (int jp = 0; jp < ip; ++jp) {
;                 const f32x2_ ta = {tr[2 * jp], tr[2 * jp]}, tb = {tr[2 * jp + 1], tr[2 * jp + 1]};
;                 const f32x2_ va = {rv[jp][0], rv[jp][1]}, vb = {rv[jp][2], rv[jp][3]};
;                 if (jp & 1) { a2 += va * ta; a3 += vb * tb; } else { a0 += va * ta; a1 += vb * tb; }
;             }
;             const f32x2_ sum = (a0 + a1) + (a2 + a3);
;             const float t0 = (lane_o == i0 ? 1.f : 0.f) - sum[0];
;             tr[i0] = t0;
;             tr[i0 + 1] = (lane_o == i0 + 1 ? 1.f : 0.f) - sum[1] - rv[ip][1] * t0;
;         }
;         const int pb = d ? 63 - lane : lane; const float sb = bS[d * 64 + pb], sbe = sb * fexp(gcS[d * 64 + pb]);
;         LAS bf16_t* T0 = Tb + d * 9216; LAS bf16_t* T1 = T0 + 4608;
; #pragma unroll
;         for (int i = 0; i < 64; ++i) { const int pa = d ? 63 - i : i; T0[pa * 72 + pb] = (bf16_t)f2bf(tr[i] * sb); T1[pa * 72 + pb] = (bf16_t)f2bf(tr[i] * sbe); }
.Lfs_row31:
	s_waitcnt lgkmcnt(0)
	v_pk_fma_f32 v[62:63], v[122:123], v[2:3], 0 op_sel_hi:[1,0,0]
	v_pk_fma_f32 v[66:67], v[124:125], v[2:3], 0 op_sel:[0,1,0] op_sel_hi:[1,1,0]
	v_pk_fma_f32 v[62:63], v[126:127], v[4:5], v[62:63] op_sel_hi:[1,0,1]
	v_pk_fma_f32 v[66:67], v[128:129], v[4:5], v[66:67] op_sel:[0,1,0] op_sel_hi:[1,1,1]
	v_pk_fma_f32 v[62:63], v[130:131], v[8:9], v[62:63] op_sel_hi:[1,0,1]
	v_pk_fma_f32 v[66:67], v[132:133], v[8:9], v[66:67] op_sel:[0,1,0] op_sel_hi:[1,1,1]
	v_pk_fma_f32 v[62:63], v[38:39], v[10:11], v[62:63] op_sel_hi:[1,0,1]
	v_pk_fma_f32 v[66:67], v[40:41], v[10:11], v[66:67] op_sel:[0,1,0] op_sel_hi:[1,1,1]
	v_pk_fma_f32 v[62:63], v[42:43], v[18:19], v[62:63] op_sel_hi:[1,0,1]
	v_pk_fma_f32 v[66:67], v[44:45], v[18:19], v[66:67] op_sel:[0,1,0] op_sel_hi:[1,1,1]
	v_pk_fma_f32 v[62:63], v[46:47], v[50:51], v[62:63] op_sel_hi:[1,0,1]
	v_pk_fma_f32 v[66:67], v[48:49], v[50:51], v[66:67] op_sel:[0,1,0] op_sel_hi:[1,1,1]
	v_pk_fma_f32 v[62:63], v[102:103], v[54:55], v[62:63] op_sel_hi:[1,0,1]
	v_pk_fma_f32 v[66:67], v[104:105], v[54:55], v[66:67] op_sel:[0,1,0] op_sel_hi:[1,1,1]
	v_pk_fma_f32 v[62:63], v[242:243], v[58:59], v[62:63] op_sel_hi:[1,0,1]
	v_pk_fma_f32 v[66:67], v[244:245], v[58:59], v[66:67] op_sel:[0,1,0] op_sel_hi:[1,1,1]
	v_pk_add_f32 v[62:63], v[62:63], v[66:67]
	s_nop 1
	v_add_f32_dpp v62, v62, v62 quad_perm:[1,0,3,2] row_mask:0xf bank_mask:0xf bound_ctrl:1
	v_add_f32_dpp v63, v63, v63 quad_perm:[1,0,3,2] row_mask:0xf bank_mask:0xf bound_ctrl:1
	s_nop 0
	v_add_f32_dpp v62, v62, v62 quad_perm:[2,3,0,1] row_mask:0xf bank_mask:0xf bound_ctrl:1
	v_add_f32_dpp v63, v63, v63 quad_perm:[2,3,0,1] row_mask:0xf bank_mask:0xf bound_ctrl:1
	s_mov_b64 exec, s[10:11]
	v_sub_f32_e32 v58, v58, v62
	v_sub_f32_e32 v59, v59, v63
	v_fma_f32 v59, v243, v62, v59
	s_mov_b64 exec, -1
	s_cmp_eq_u32 s1, 0
	s_cbranch_scc0 .Lfs_out1
	v_pk_mul_f32 v[114:115], v[2:3], v[56:57] op_sel_hi:[1,0]
	v_pk_mul_f32 v[118:119], v[2:3], v[60:61] op_sel_hi:[1,0]
	v_cvt_pk_bf16_f32 v174, v114, v115
	v_cvt_pk_bf16_f32 v175, v118, v119
	ds_write_b16 v64, v174
	ds_write_b16_d16_hi v64, v174 offset:144
	ds_write_b16 v64, v175 offset:9216
	ds_write_b16_d16_hi v64, v175 offset:9360
	v_pk_mul_f32 v[114:115], v[4:5], v[56:57] op_sel_hi:[1,0]
	v_pk_mul_f32 v[118:119], v[4:5], v[60:61] op_sel_hi:[1,0]
	v_cvt_pk_bf16_f32 v174, v114, v115
	v_cvt_pk_bf16_f32 v175, v118, v119
	ds_write_b16 v64, v174 offset:1152
	ds_write_b16_d16_hi v64, v174 offset:1296
	ds_write_b16 v64, v175 offset:10368
	ds_write_b16_d16_hi v64, v175 offset:10512
	v_pk_mul_f32 v[114:115], v[8:9], v[56:57] op_sel_hi:[1,0]
	v_pk_mul_f32 v[118:119], v[8:9], v[60:61] op_sel_hi:[1,0]
	v_cvt_pk_bf16_f32 v174, v114, v115
	v_cvt_pk_bf16_f32 v175, v118, v119
	ds_write_b16 v64, v174 offset:2304
	ds_write_b16_d16_hi v64, v174 offset:2448
	ds_write_b16 v64, v175 offset:11520
	ds_write_b16_d16_hi v64, v175 offset:11664
	v_pk_mul_f32 v[114:115], v[10:11], v[56:57] op_sel_hi:[1,0]
	v_pk_mul_f32 v[118:119], v[10:11], v[60:61] op_sel_hi:[1,0]
	v_cvt_pk_bf16_f32 v174, v114, v115
	v_cvt_pk_bf16_f32 v175, v118, v119
	ds_write_b16 v64, v174 offset:3456
	ds_write_b16_d16_hi v64, v174 offset:3600
	ds_write_b16 v64, v175 offset:12672
	ds_write_b16_d16_hi v64, v175 offset:12816
	v_pk_mul_f32 v[114:115], v[18:19], v[56:57] op_sel_hi:[1,0]
	v_pk_mul_f32 v[118:119], v[18:19], v[60:61] op_sel_hi:[1,0]
	v_cvt_pk_bf16_f32 v174, v114, v115
	v_cvt_pk_bf16_f32 v175, v118, v119
	ds_write_b16 v64, v174 offset:4608
	ds_write_b16_d16_hi v64, v174 offset:4752
	ds_write_b16 v64, v175 offset:13824
	ds_write_b16_d16_hi v64, v175 offset:13968
	v_pk_mul_f32 v[114:115], v[50:51], v[56:57] op_sel_hi:[1,0]
	v_pk_mul_f32 v[118:119], v[50:51], v[60:61] op_sel_hi:[1,0]
	v_cvt_pk_bf16_f32 v174, v114, v115
	v_cvt_pk_bf16_f32 v175, v118, v119
	ds_write_b16 v64, v174 offset:5760
	ds_write_b16_d16_hi v64, v174 offset:5904
	ds_write_b16 v64, v175 offset:14976
	ds_write_b16_d16_hi v64, v175 offset:15120
	v_pk_mul_f32 v[114:115], v[54:55], v[56:57] op_sel_hi:[1,0]
	v_pk_mul_f32 v[118:119], v[54:55], v[60:61] op_sel_hi:[1,0]
	v_cvt_pk_bf16_f32 v174, v114, v115
	v_cvt_pk_bf16_f32 v175, v118, v119
	ds_write_b16 v64, v174 offset:6912
	ds_write_b16_d16_hi v64, v174 offset:7056
	ds_write_b16 v64, v175 offset:16128
	ds_write_b16_d16_hi v64, v175 offset:16272
	v_pk_mul_f32 v[114:115], v[58:59], v[56:57] op_sel_hi:[1,0]
	v_pk_mul_f32 v[118:119], v[58:59], v[60:61] op_sel_hi:[1,0]
	v_cvt_pk_bf16_f32 v174, v114, v115
	v_cvt_pk_bf16_f32 v175, v118, v119
	ds_write_b16 v64, v174 offset:8064
	ds_write_b16_d16_hi v64, v174 offset:8208
	ds_write_b16 v64, v175 offset:17280
	ds_write_b16_d16_hi v64, v175 offset:17424
	s_branch .Lfs_done
